# K-loop load segments of all four GEMM phases: LDS-DMA issued through the SGPR-base form (the per-tile v_lshl_add_u64 address arithmetic replaced by a few SALU adds), loop-invariant ds_read base regist
# speedup vs baseline: 1.0120x; 1.0031x over previous
; #define PG8_STAGE(bufoff, gbase, voff) do { _Pragma("unroll") for (int _i = 0; _i < 2; ++_i) \
;         __builtin_amdgcn_global_load_lds((const unsigned*)((const char*)(gbase) + (voff)[_i]), (PG8_LAS unsigned*)(lds + (bufoff) + ldsw + _i * 8192), 16, 0, 0); } while (0)
; #define PG8_LDA(dst, b, h) do { _Pragma("unroll") for (int m = 0; m < 4; ++m) _Pragma("unroll") for (int k = 0; k < 2; ++k) dst[m][k] = *(const PG8_LAS bf16x8*)(lds + PG8_SA(b, h) + aoff + m * 2048 + k * 1024); } while (0)
; #define PG8_LDB(dst, b, h) do { _Pragma("unroll") for (int n = 0; n < 2; ++n) _Pragma("unroll") for (int k = 0; k < 2; ++k) dst[n][k] = *(const PG8_LAS bf16x8*)(lds + PG8_SB(b, h) + boff + n * 2048 + k * 1024); } while (0)
; #define PG8_WAIT_V(n) asm volatile("s_waitcnt vmcnt(" #n ")" ::: "memory")
; #define PG8_WAIT_L(n) asm volatile("s_waitcnt lgkmcnt(" #n ")" ::: "memory")
; template <class Epi, class Sched, bool ALIGN_EPI = false, bool SP2 = false>
; __device__ __forceinline__ void gemm_phase(PG8_LAS unsigned char* lds, const Gemm g, const Sched& S, const Epi& E) {
;     ...
;         const bool has_next = S.next(ui + 1, nxt);
;         const char* nA = has_next ? (const char*)g.A + (size_t)nxt.pm * tstep : cA; const char* nB = has_next ? (const char*)g.Bt + (size_t)nxt.pn * tstep : cB;
;         for (int t = 0; t < nt; t += 2) {
;             const bool last = (t == nt - 2);
;             const char* a1 = cA + (size_t)(t + 1) * kstep;
;             const char* a2 = last ? nA : cA + (size_t)(t + 2) * kstep; const char* b2 = last ? nB : cB + (size_t)(t + 2) * kstep;
;             const char* a3 = a2 + kstep; const char* b3 = b2 + kstep;
;             if (last && has_next) S.a_ready(nxt);
;             if constexpr (Epi::KSPLIT) { if (t == (nt >> 1)) E.mid(acc, cur, wr, wc, fr, fq); }
;             if constexpr (SP2) {
;             PG8_LDB(B0, 0, 0); PG8_LDB(B1, 0, 1); PG8_SCHED; PG8_LDA(At, 0, 0); PG8_STAGE(PG8_SA(1, 1), a1 + hstep, voffA);
;             PG8_WAIT_V(8); PG8_WAIT_L(0); PG8_BAR; PG8_MMA(0, 0, At, B0); PG8_MMA(0, 1, At, B1); PG8_BAR; PG8_SCHED;
;     ...
;         for (int a = 0; a < 2; ++a)
; #pragma unroll
;             for (int b = 0; b < 2; ++b)
; #pragma unroll
;                 for (int m = 0; m < 4; ++m)
; #pragma unroll
;                     for (int n = 0; n < 2; ++n) acc[a][b][m][n] = (f32x4){0.f, 0.f, 0.f, 0.f};
;         cur = nxt; cA = nA; cB = nB; ++ui;
.LBB0_173:
	s_add_i32 s51, s51, 1
	s_mov_b64 s[2:3], s[6:7]
	s_mov_b32 s53, s14
	s_lshl_b32 s6, s51, 3
	v_readlane_b32 s14, v248, 25
	s_add_i32 s14, s6, s14
	v_readlane_b32 s15, v248, 26
	s_cmp_lt_i32 s14, 14
	s_cselect_b64 s[38:39], -1, 0
	s_ashr_i32 s15, s14, 31
	s_lshl_b64 s[6:7], s[14:15], 20
	s_add_u32 s6, s44, s6
	s_addc_u32 s7, s45, s7
	s_and_b64 s[36:37], s[38:39], exec
	v_mov_b32_e32 v4, 0
	s_cselect_b32 s15, s7, s3
	s_cselect_b32 s52, s6, s2
	s_mov_b32 s54, -2
	s_mov_b64 s[2:3], 0
	v_mov_b32_e32 v5, v4
	v_mov_b32_e32 v6, v4
	v_mov_b32_e32 v7, v4
	v_mov_b32_e32 v8, v4
	v_mov_b32_e32 v9, v4
	v_mov_b32_e32 v10, v4
	v_mov_b32_e32 v11, v4
	v_mov_b32_e32 v20, v4
	v_mov_b32_e32 v21, v4
	v_mov_b32_e32 v22, v4
	v_mov_b32_e32 v23, v4
	v_mov_b32_e32 v24, v4
	v_mov_b32_e32 v25, v4
	v_mov_b32_e32 v26, v4
	v_mov_b32_e32 v27, v4
	v_mov_b32_e32 v36, v4
	v_mov_b32_e32 v37, v4
	v_mov_b32_e32 v38, v4
	v_mov_b32_e32 v39, v4
	v_mov_b32_e32 v40, v4
	v_mov_b32_e32 v41, v4
	v_mov_b32_e32 v42, v4
	v_mov_b32_e32 v43, v4
	v_mov_b32_e32 v52, v4
	v_mov_b32_e32 v53, v4
	v_mov_b32_e32 v54, v4
	v_mov_b32_e32 v55, v4
	v_mov_b32_e32 v56, v4
	v_mov_b32_e32 v57, v4
	v_mov_b32_e32 v58, v4
	v_mov_b32_e32 v59, v4
	v_mov_b32_e32 v12, v4
	v_mov_b32_e32 v13, v4
	v_mov_b32_e32 v14, v4
	v_mov_b32_e32 v15, v4
	v_mov_b32_e32 v16, v4
	v_mov_b32_e32 v17, v4
	v_mov_b32_e32 v18, v4
	v_mov_b32_e32 v19, v4
	v_mov_b32_e32 v28, v4
	v_mov_b32_e32 v29, v4
	v_mov_b32_e32 v30, v4
	v_mov_b32_e32 v31, v4
	v_mov_b32_e32 v32, v4
	v_mov_b32_e32 v33, v4
	v_mov_b32_e32 v34, v4
	v_mov_b32_e32 v35, v4
	v_mov_b32_e32 v44, v4
	v_mov_b32_e32 v45, v4
	v_mov_b32_e32 v46, v4
	v_mov_b32_e32 v47, v4
	v_mov_b32_e32 v48, v4
	v_mov_b32_e32 v49, v4
	v_mov_b32_e32 v50, v4
	v_mov_b32_e32 v51, v4
	v_mov_b32_e32 v60, v4
	v_mov_b32_e32 v61, v4
	v_mov_b32_e32 v62, v4
	v_mov_b32_e32 v63, v4
	v_mov_b32_e32 v64, v4
	v_mov_b32_e32 v65, v4
	v_mov_b32_e32 v66, v4
	v_mov_b32_e32 v67, v4
	v_mov_b32_e32 v68, v4
	v_mov_b32_e32 v69, v4
	v_mov_b32_e32 v70, v4
	v_mov_b32_e32 v71, v4
	v_mov_b32_e32 v72, v4
	v_mov_b32_e32 v73, v4
	v_mov_b32_e32 v74, v4
	v_mov_b32_e32 v75, v4
	v_mov_b32_e32 v84, v4
	v_mov_b32_e32 v85, v4
	v_mov_b32_e32 v86, v4
	v_mov_b32_e32 v87, v4
	v_mov_b32_e32 v88, v4
	v_mov_b32_e32 v89, v4
	v_mov_b32_e32 v90, v4
	v_mov_b32_e32 v91, v4
	v_mov_b32_e32 v100, v4
	v_mov_b32_e32 v101, v4
	v_mov_b32_e32 v102, v4
	v_mov_b32_e32 v103, v4
	v_mov_b32_e32 v104, v4
	v_mov_b32_e32 v105, v4
	v_mov_b32_e32 v106, v4
	v_mov_b32_e32 v107, v4
	v_mov_b32_e32 v116, v4
	v_mov_b32_e32 v117, v4
	v_mov_b32_e32 v118, v4
	v_mov_b32_e32 v119, v4
	v_mov_b32_e32 v120, v4
	v_mov_b32_e32 v121, v4
	v_mov_b32_e32 v122, v4
	v_mov_b32_e32 v123, v4
	v_mov_b32_e32 v76, v4
	v_mov_b32_e32 v77, v4
	v_mov_b32_e32 v78, v4
	v_mov_b32_e32 v79, v4
	v_mov_b32_e32 v80, v4
	v_mov_b32_e32 v81, v4
	v_mov_b32_e32 v82, v4
	v_mov_b32_e32 v83, v4
	v_mov_b32_e32 v92, v4
	v_mov_b32_e32 v93, v4
	v_mov_b32_e32 v94, v4
	v_mov_b32_e32 v95, v4
	v_mov_b32_e32 v96, v4
	v_mov_b32_e32 v97, v4
	v_mov_b32_e32 v98, v4
	v_mov_b32_e32 v99, v4
	v_mov_b32_e32 v108, v4
	v_mov_b32_e32 v109, v4
	v_mov_b32_e32 v110, v4
	v_mov_b32_e32 v111, v4
	v_mov_b32_e32 v112, v4
	v_mov_b32_e32 v113, v4
	v_mov_b32_e32 v114, v4
	v_mov_b32_e32 v115, v4
	v_mov_b32_e32 v124, v4
	v_mov_b32_e32 v125, v4
	v_mov_b32_e32 v126, v4
	v_mov_b32_e32 v127, v4
	v_mov_b32_e32 v128, v4
	v_mov_b32_e32 v129, v4
	v_mov_b32_e32 v130, v4
	v_mov_b32_e32 v131, v4
	v_add_u32_e32 v168, 0x10000, v3
	v_add_u32_e32 v169, 0x14000, v3
	v_add_u32_e32 v170, 0x18000, v3
	v_add_u32_e32 v171, 0x1c000, v3
.LBB0_174:
	s_add_u32 s36, s31, s2
	s_addc_u32 s37, s91, s3
	s_add_u32 s36, s36, 0x16200100
	s_addc_u32 s37, s37, 0
	s_add_u32 s55, s12, s2
	s_addc_u32 s56, s13, s3
	s_add_i32 s57, 0, 0x10000
	s_cmpk_eq_i32 s2, 0xf00
	s_cselect_b32 s41, s1, s37
	s_cselect_b32 s40, s0, s36
	s_cselect_b32 s37, s15, s56
	s_cselect_b32 s36, s52, s55
	s_add_i32 s55, 0, 0x14000
	ds_read_b128 v[142:145], v168
	ds_read_b128 v[146:149], v168 offset:1024
	ds_read_b128 v[156:159], v168 offset:2048
	ds_read_b128 v[172:175], v168 offset:3072
	ds_read_b128 v[176:179], v169
	ds_read_b128 v[180:183], v169 offset:1024
	ds_read_b128 v[184:187], v169 offset:2048
	ds_read_b128 v[188:191], v169 offset:3072
	v_lshl_add_u64 v[150:151], v[138:139], 0, s[2:3]
	s_add_i32 m0, s43, 0xc000
	ds_read_b128 v[192:195], v154
	ds_read_b128 v[196:199], v154 offset:1024
	ds_read_b128 v[200:203], v154 offset:2048
	ds_read_b128 v[212:215], v154 offset:3072
	ds_read_b128 v[216:219], v154 offset:4096
	ds_read_b128 v[220:223], v154 offset:5120
	ds_read_b128 v[224:227], v154 offset:6144
	ds_read_b128 v[228:231], v154 offset:7168
	global_load_lds_dwordx4 v[150:151], off
	v_lshl_add_u64 v[150:151], v[140:141], 0, s[2:3]
	s_add_i32 m0, s43, 0xe000
	s_nop 0
	global_load_lds_dwordx4 v[150:151], off
	s_waitcnt vmcnt(8)
	s_waitcnt lgkmcnt(0)
	s_barrier
; #define PG8_STAGE(bufoff, gbase, voff) do { _Pragma("unroll") for (int _i = 0; _i < 2; ++_i) \
;         __builtin_amdgcn_global_load_lds((const unsigned*)((const char*)(gbase) + (voff)[_i]), (PG8_LAS unsigned*)(lds + (bufoff) + ldsw + _i * 8192), 16, 0, 0); } while (0)
; #define PG8_LDA(dst, b, h) do { _Pragma("unroll") for (int m = 0; m < 4; ++m) _Pragma("unroll") for (int k = 0; k < 2; ++k) dst[m][k] = *(const PG8_LAS bf16x8*)(lds + PG8_SA(b, h) + aoff + m * 2048 + k * 1024); } while (0)
; #define PG8_LDB(dst, b, h) do { _Pragma("unroll") for (int n = 0; n < 2; ++n) _Pragma("unroll") for (int k = 0; k < 2; ++k) dst[n][k] = *(const PG8_LAS bf16x8*)(lds + PG8_SB(b, h) + boff + n * 2048 + k * 1024); } while (0)
; #define PG8_MMA(ai, bj, At, Bt) do { __builtin_amdgcn_s_setprio(1); _Pragma("unroll") for (int m = 0; m < 4; ++m) _Pragma("unroll") for (int n = 0; n < 2; ++n) _Pragma("unroll") for (int k = 0; k < 2; ++k) \
;         acc[ai][bj][m][n] = __builtin_amdgcn_mfma_f32_16x16x32_bf16(Bt[n][k], At[m][k], acc[ai][bj][m][n], 0, 0, 0); __builtin_amdgcn_s_setprio(0); } while (0)
; #define PG8_WAIT_V(n) asm volatile("s_waitcnt vmcnt(" #n ")" ::: "memory")
; #define PG8_WAIT_L(n) asm volatile("s_waitcnt lgkmcnt(" #n ")" ::: "memory")
; #define PG8_BAR __builtin_amdgcn_s_barrier()
; #define PG8_SCHED __builtin_amdgcn_sched_barrier(0)
; template <class Epi, class Sched, bool ALIGN_EPI = false, bool SP2 = false>
; __device__ __forceinline__ void gemm_phase(PG8_LAS unsigned char* lds, const Gemm g, const Sched& S, const Epi& E) {
;     ...
;             PG8_LDB(B0, 0, 0); PG8_LDB(B1, 0, 1); PG8_SCHED; PG8_LDA(At, 0, 0); PG8_STAGE(PG8_SA(1, 1), a1 + hstep, voffA);
;             PG8_WAIT_V(8); PG8_WAIT_L(0); PG8_BAR; PG8_MMA(0, 0, At, B0); PG8_MMA(0, 1, At, B1); PG8_BAR; PG8_SCHED;
;             PG8_LDA(At, 0, 1); PG8_STAGE(PG8_SB(0, 0), b2, voffB); PG8_STAGE(PG8_SB(0, 1), b2 + hstep, voffB); PG8_STAGE(PG8_SA(0, 0), a2, voffA);
;             PG8_WAIT_V(8); PG8_WAIT_L(0); PG8_BAR; PG8_MMA(1, 0, At, B0); PG8_MMA(1, 1, At, B1); PG8_BAR; PG8_SCHED;
	s_setprio 1
	s_waitcnt lgkmcnt(0)
	v_mfma_f32_16x16x32_bf16 v[128:131], v[142:145], v[192:195], v[128:131]
	v_mfma_f32_16x16x32_bf16 v[124:127], v[156:159], v[192:195], v[124:127]
	v_mfma_f32_16x16x32_bf16 v[112:115], v[142:145], v[200:203], v[112:115]
	v_mfma_f32_16x16x32_bf16 v[108:111], v[156:159], v[200:203], v[108:111]
	v_mfma_f32_16x16x32_bf16 v[96:99], v[142:145], v[216:219], v[96:99]
	v_mfma_f32_16x16x32_bf16 v[92:95], v[156:159], v[216:219], v[92:95]
	v_mfma_f32_16x16x32_bf16 v[80:83], v[142:145], v[224:227], v[80:83]
	v_mfma_f32_16x16x32_bf16 v[76:79], v[156:159], v[224:227], v[76:79]
	v_mfma_f32_16x16x32_bf16 v[128:131], v[146:149], v[196:199], v[128:131]
	v_mfma_f32_16x16x32_bf16 v[124:127], v[172:175], v[196:199], v[124:127]
	v_mfma_f32_16x16x32_bf16 v[112:115], v[146:149], v[212:215], v[112:115]
	v_mfma_f32_16x16x32_bf16 v[108:111], v[172:175], v[212:215], v[108:111]
	v_mfma_f32_16x16x32_bf16 v[96:99], v[146:149], v[220:223], v[96:99]
	v_mfma_f32_16x16x32_bf16 v[92:95], v[172:175], v[220:223], v[92:95]
	v_mfma_f32_16x16x32_bf16 v[80:83], v[146:149], v[228:231], v[80:83]
	v_mfma_f32_16x16x32_bf16 v[76:79], v[172:175], v[228:231], v[76:79]
	s_setprio 0
	s_setprio 1
	v_mfma_f32_16x16x32_bf16 v[120:123], v[176:179], v[192:195], v[120:123]
	v_mfma_f32_16x16x32_bf16 v[116:119], v[184:187], v[192:195], v[116:119]
	v_mfma_f32_16x16x32_bf16 v[104:107], v[176:179], v[200:203], v[104:107]
	v_mfma_f32_16x16x32_bf16 v[100:103], v[184:187], v[200:203], v[100:103]
	v_mfma_f32_16x16x32_bf16 v[88:91], v[176:179], v[216:219], v[88:91]
	v_mfma_f32_16x16x32_bf16 v[84:87], v[184:187], v[216:219], v[84:87]
	v_mfma_f32_16x16x32_bf16 v[72:75], v[176:179], v[224:227], v[72:75]
	v_mfma_f32_16x16x32_bf16 v[68:71], v[184:187], v[224:227], v[68:71]
	v_mfma_f32_16x16x32_bf16 v[120:123], v[180:183], v[196:199], v[120:123]
	v_mfma_f32_16x16x32_bf16 v[116:119], v[188:191], v[196:199], v[116:119]
	v_mfma_f32_16x16x32_bf16 v[104:107], v[180:183], v[212:215], v[104:107]
	v_mfma_f32_16x16x32_bf16 v[100:103], v[188:191], v[212:215], v[100:103]
	v_mfma_f32_16x16x32_bf16 v[88:91], v[180:183], v[220:223], v[88:91]
	v_mfma_f32_16x16x32_bf16 v[84:87], v[188:191], v[220:223], v[84:87]
	v_mfma_f32_16x16x32_bf16 v[72:75], v[180:183], v[228:231], v[72:75]
	v_mfma_f32_16x16x32_bf16 v[68:71], v[188:191], v[228:231], v[68:71]
	s_setprio 0
	s_barrier
	s_add_i32 s56, s57, s42
	s_add_u32 s98, s36, 0x80
	s_addc_u32 s99, s37, 0
	s_mov_b32 m0, s56
	ds_read_b128 v[192:195], v154 offset:16384
	ds_read_b128 v[196:199], v154 offset:17408
	ds_read_b128 v[200:203], v154 offset:18432
	ds_read_b128 v[212:215], v154 offset:19456
	ds_read_b128 v[216:219], v154 offset:20480
	ds_read_b128 v[220:223], v154 offset:21504
	ds_read_b128 v[224:227], v154 offset:22528
	ds_read_b128 v[228:231], v154 offset:23552
	global_load_lds_dwordx4 v134, s[36:37]
	s_add_i32 m0, s56, 0x2000
	s_add_u32 s56, s36, 0x80000
	s_addc_u32 s57, s37, 0
	s_add_i32 s55, s55, s42
	global_load_lds_dwordx4 v0, s[36:37]
	s_mov_b32 m0, s55
	s_add_u32 s100, s40, 0x80
	s_addc_u32 s101, s41, 0
	s_nop 0
	global_load_lds_dwordx4 v134, s[56:57]
	s_add_i32 m0, s55, 0x2000
	s_nop 0
	global_load_lds_dwordx4 v0, s[56:57]
	s_mov_b32 m0, s43
	s_nop 0
	global_load_lds_dwordx4 v136, s[40:41]
	s_mov_b32 m0, s46
	s_nop 0
	global_load_lds_dwordx4 v132, s[40:41]
	s_waitcnt vmcnt(8)
	s_waitcnt lgkmcnt(0)
	s_barrier
	s_setprio 1
	s_waitcnt lgkmcnt(0)
	v_mfma_f32_16x16x32_bf16 v[64:67], v[142:145], v[192:195], v[64:67]
	v_mfma_f32_16x16x32_bf16 v[60:63], v[156:159], v[192:195], v[60:63]
	v_mfma_f32_16x16x32_bf16 v[48:51], v[142:145], v[200:203], v[48:51]
	v_mfma_f32_16x16x32_bf16 v[44:47], v[156:159], v[200:203], v[44:47]
	v_mfma_f32_16x16x32_bf16 v[32:35], v[142:145], v[216:219], v[32:35]
	v_mfma_f32_16x16x32_bf16 v[28:31], v[156:159], v[216:219], v[28:31]
	v_mfma_f32_16x16x32_bf16 v[16:19], v[142:145], v[224:227], v[16:19]
	v_mfma_f32_16x16x32_bf16 v[12:15], v[156:159], v[224:227], v[12:15]
	v_mfma_f32_16x16x32_bf16 v[64:67], v[146:149], v[196:199], v[64:67]
	v_mfma_f32_16x16x32_bf16 v[60:63], v[172:175], v[196:199], v[60:63]
	v_mfma_f32_16x16x32_bf16 v[48:51], v[146:149], v[212:215], v[48:51]
	v_mfma_f32_16x16x32_bf16 v[44:47], v[172:175], v[212:215], v[44:47]
	v_mfma_f32_16x16x32_bf16 v[32:35], v[146:149], v[220:223], v[32:35]
	v_mfma_f32_16x16x32_bf16 v[28:31], v[172:175], v[220:223], v[28:31]
	v_mfma_f32_16x16x32_bf16 v[16:19], v[146:149], v[228:231], v[16:19]
	v_mfma_f32_16x16x32_bf16 v[12:15], v[172:175], v[228:231], v[12:15]
	s_setprio 0
	s_setprio 1
	v_mfma_f32_16x16x32_bf16 v[56:59], v[176:179], v[192:195], v[56:59]
	v_mfma_f32_16x16x32_bf16 v[52:55], v[184:187], v[192:195], v[52:55]
	v_mfma_f32_16x16x32_bf16 v[40:43], v[176:179], v[200:203], v[40:43]
	v_mfma_f32_16x16x32_bf16 v[36:39], v[184:187], v[200:203], v[36:39]
	v_mfma_f32_16x16x32_bf16 v[24:27], v[176:179], v[216:219], v[24:27]
	v_mfma_f32_16x16x32_bf16 v[20:23], v[184:187], v[216:219], v[20:23]
	v_mfma_f32_16x16x32_bf16 v[8:11], v[176:179], v[224:227], v[8:11]
	v_mfma_f32_16x16x32_bf16 v[4:7], v[184:187], v[224:227], v[4:7]
	v_mfma_f32_16x16x32_bf16 v[56:59], v[180:183], v[196:199], v[56:59]
	v_mfma_f32_16x16x32_bf16 v[52:55], v[188:191], v[196:199], v[52:55]
	v_mfma_f32_16x16x32_bf16 v[40:43], v[180:183], v[212:215], v[40:43]
	v_mfma_f32_16x16x32_bf16 v[36:39], v[188:191], v[212:215], v[36:39]
	v_mfma_f32_16x16x32_bf16 v[24:27], v[180:183], v[220:223], v[24:27]
	v_mfma_f32_16x16x32_bf16 v[20:23], v[188:191], v[220:223], v[20:23]
	v_mfma_f32_16x16x32_bf16 v[8:11], v[180:183], v[228:231], v[8:11]
	v_mfma_f32_16x16x32_bf16 v[4:7], v[188:191], v[228:231], v[4:7]
	s_setprio 0
	s_barrier
; #define PG8_STAGE(bufoff, gbase, voff) do { _Pragma("unroll") for (int _i = 0; _i < 2; ++_i) \
;         __builtin_amdgcn_global_load_lds((const unsigned*)((const char*)(gbase) + (voff)[_i]), (PG8_LAS unsigned*)(lds + (bufoff) + ldsw + _i * 8192), 16, 0, 0); } while (0)
; #define PG8_LDA(dst, b, h) do { _Pragma("unroll") for (int m = 0; m < 4; ++m) _Pragma("unroll") for (int k = 0; k < 2; ++k) dst[m][k] = *(const PG8_LAS bf16x8*)(lds + PG8_SA(b, h) + aoff + m * 2048 + k * 1024); } while (0)
; #define PG8_LDB(dst, b, h) do { _Pragma("unroll") for (int n = 0; n < 2; ++n) _Pragma("unroll") for (int k = 0; k < 2; ++k) dst[n][k] = *(const PG8_LAS bf16x8*)(lds + PG8_SB(b, h) + boff + n * 2048 + k * 1024); } while (0)
; #define PG8_MMA(ai, bj, At, Bt) do { __builtin_amdgcn_s_setprio(1); _Pragma("unroll") for (int m = 0; m < 4; ++m) _Pragma("unroll") for (int n = 0; n < 2; ++n) _Pragma("unroll") for (int k = 0; k < 2; ++k) \
;         acc[ai][bj][m][n] = __builtin_amdgcn_mfma_f32_16x16x32_bf16(Bt[n][k], At[m][k], acc[ai][bj][m][n], 0, 0, 0); __builtin_amdgcn_s_setprio(0); } while (0)
; #define PG8_WAIT_V(n) asm volatile("s_waitcnt vmcnt(" #n ")" ::: "memory")
; #define PG8_WAIT_L(n) asm volatile("s_waitcnt lgkmcnt(" #n ")" ::: "memory")
; #define PG8_BAR __builtin_amdgcn_s_barrier()
; #define PG8_SCHED __builtin_amdgcn_sched_barrier(0)
; template <class Epi, class Sched, bool ALIGN_EPI = false, bool SP2 = false>
; __device__ __forceinline__ void gemm_phase(PG8_LAS unsigned char* lds, const Gemm g, const Sched& S, const Epi& E) {
;     ...
;             PG8_WAIT_V(8); PG8_WAIT_L(0); PG8_BAR; PG8_MMA(1, 0, At, B0); PG8_MMA(1, 1, At, B1); PG8_BAR; PG8_SCHED;
;             PG8_LDB(B0, 1, 0); PG8_LDB(B1, 1, 1); PG8_SCHED; PG8_LDA(At, 1, 0); PG8_STAGE(PG8_SA(0, 1), a2 + hstep, voffA);
;             PG8_WAIT_V(8); PG8_WAIT_L(0); PG8_BAR; PG8_MMA(0, 0, At, B0); PG8_MMA(0, 1, At, B1); PG8_BAR; PG8_SCHED;
;             PG8_LDA(At, 1, 1); PG8_STAGE(PG8_SB(1, 0), b3, voffB); PG8_STAGE(PG8_SB(1, 1), b3 + hstep, voffB); PG8_STAGE(PG8_SA(1, 0), a3, voffA);
;             PG8_WAIT_V(8); PG8_WAIT_L(0); PG8_BAR; PG8_MMA(1, 0, At, B0); PG8_MMA(1, 1, At, B1); PG8_BAR; PG8_SCHED;
	s_add_i32 s55, 0, 0x18000
	s_add_i32 s56, 0, 0x1c000
	ds_read_b128 v[142:145], v170
	ds_read_b128 v[146:149], v170 offset:1024
	ds_read_b128 v[156:159], v170 offset:2048
	ds_read_b128 v[172:175], v170 offset:3072
	ds_read_b128 v[176:179], v171
	ds_read_b128 v[180:183], v171 offset:1024
	ds_read_b128 v[184:187], v171 offset:2048
	ds_read_b128 v[188:191], v171 offset:3072
	s_add_u32 s40, s40, 0x80000
	s_addc_u32 s41, s41, 0
	s_mov_b32 m0, s47
	ds_read_b128 v[192:195], v154 offset:32768
	ds_read_b128 v[196:199], v154 offset:33792
	ds_read_b128 v[200:203], v154 offset:34816
	ds_read_b128 v[212:215], v154 offset:35840
	ds_read_b128 v[216:219], v154 offset:36864
	ds_read_b128 v[220:223], v154 offset:37888
	ds_read_b128 v[224:227], v154 offset:38912
	ds_read_b128 v[228:231], v154 offset:39936
	global_load_lds_dwordx4 v136, s[40:41]
	s_mov_b32 m0, s48
	s_nop 0
	global_load_lds_dwordx4 v132, s[40:41]
	s_waitcnt vmcnt(8)
	s_waitcnt lgkmcnt(0)
	s_barrier
	s_setprio 1
	s_waitcnt lgkmcnt(0)
	v_mfma_f32_16x16x32_bf16 v[128:131], v[142:145], v[192:195], v[128:131]
	v_mfma_f32_16x16x32_bf16 v[124:127], v[156:159], v[192:195], v[124:127]
	v_mfma_f32_16x16x32_bf16 v[112:115], v[142:145], v[200:203], v[112:115]
	v_mfma_f32_16x16x32_bf16 v[108:111], v[156:159], v[200:203], v[108:111]
	v_mfma_f32_16x16x32_bf16 v[96:99], v[142:145], v[216:219], v[96:99]
	v_mfma_f32_16x16x32_bf16 v[92:95], v[156:159], v[216:219], v[92:95]
	v_mfma_f32_16x16x32_bf16 v[80:83], v[142:145], v[224:227], v[80:83]
	v_mfma_f32_16x16x32_bf16 v[76:79], v[156:159], v[224:227], v[76:79]
	v_mfma_f32_16x16x32_bf16 v[128:131], v[146:149], v[196:199], v[128:131]
	v_mfma_f32_16x16x32_bf16 v[124:127], v[172:175], v[196:199], v[124:127]
	v_mfma_f32_16x16x32_bf16 v[112:115], v[146:149], v[212:215], v[112:115]
	v_mfma_f32_16x16x32_bf16 v[108:111], v[172:175], v[212:215], v[108:111]
	v_mfma_f32_16x16x32_bf16 v[96:99], v[146:149], v[220:223], v[96:99]
	v_mfma_f32_16x16x32_bf16 v[92:95], v[172:175], v[220:223], v[92:95]
	v_mfma_f32_16x16x32_bf16 v[80:83], v[146:149], v[228:231], v[80:83]
	v_mfma_f32_16x16x32_bf16 v[76:79], v[172:175], v[228:231], v[76:79]
	s_setprio 0
	s_setprio 1
	v_mfma_f32_16x16x32_bf16 v[120:123], v[176:179], v[192:195], v[120:123]
	v_mfma_f32_16x16x32_bf16 v[116:119], v[184:187], v[192:195], v[116:119]
	v_mfma_f32_16x16x32_bf16 v[104:107], v[176:179], v[200:203], v[104:107]
	v_mfma_f32_16x16x32_bf16 v[100:103], v[184:187], v[200:203], v[100:103]
	v_mfma_f32_16x16x32_bf16 v[88:91], v[176:179], v[216:219], v[88:91]
	v_mfma_f32_16x16x32_bf16 v[84:87], v[184:187], v[216:219], v[84:87]
	v_mfma_f32_16x16x32_bf16 v[72:75], v[176:179], v[224:227], v[72:75]
	v_mfma_f32_16x16x32_bf16 v[68:71], v[184:187], v[224:227], v[68:71]
	v_mfma_f32_16x16x32_bf16 v[120:123], v[180:183], v[196:199], v[120:123]
	v_mfma_f32_16x16x32_bf16 v[116:119], v[188:191], v[196:199], v[116:119]
	v_mfma_f32_16x16x32_bf16 v[104:107], v[180:183], v[212:215], v[104:107]
	v_mfma_f32_16x16x32_bf16 v[100:103], v[188:191], v[212:215], v[100:103]
	v_mfma_f32_16x16x32_bf16 v[88:91], v[180:183], v[220:223], v[88:91]
	v_mfma_f32_16x16x32_bf16 v[84:87], v[188:191], v[220:223], v[84:87]
	v_mfma_f32_16x16x32_bf16 v[72:75], v[180:183], v[228:231], v[72:75]
	v_mfma_f32_16x16x32_bf16 v[68:71], v[188:191], v[228:231], v[68:71]
	s_setprio 0
	s_barrier
	s_add_i32 s40, s55, s42
	s_mov_b32 m0, s40
	ds_read_b128 v[192:195], v154 offset:49152
	ds_read_b128 v[196:199], v154 offset:50176
	ds_read_b128 v[200:203], v154 offset:51200
	ds_read_b128 v[212:215], v154 offset:52224
	ds_read_b128 v[216:219], v154 offset:53248
	ds_read_b128 v[220:223], v154 offset:54272
	ds_read_b128 v[224:227], v154 offset:55296
	ds_read_b128 v[228:231], v154 offset:56320
	global_load_lds_dwordx4 v134, s[98:99]
	s_add_i32 m0, s40, 0x2000
	s_add_u32 s36, s36, 0x80080
	s_addc_u32 s37, s37, 0
	s_add_i32 s40, s56, s42
	global_load_lds_dwordx4 v0, s[98:99]
	s_mov_b32 m0, s40
	s_nop 0
	global_load_lds_dwordx4 v134, s[36:37]
	s_add_i32 m0, s40, 0x2000
	s_nop 0
	global_load_lds_dwordx4 v0, s[36:37]
	s_mov_b32 m0, s49
	s_nop 0
	global_load_lds_dwordx4 v136, s[100:101]
	s_mov_b32 m0, s50
	s_nop 0
	global_load_lds_dwordx4 v132, s[100:101]
	s_waitcnt vmcnt(8)
	s_waitcnt lgkmcnt(0)
	s_barrier
	s_setprio 1
	s_waitcnt lgkmcnt(0)
	v_mfma_f32_16x16x32_bf16 v[64:67], v[142:145], v[192:195], v[64:67]
	v_mfma_f32_16x16x32_bf16 v[60:63], v[156:159], v[192:195], v[60:63]
	v_mfma_f32_16x16x32_bf16 v[48:51], v[142:145], v[200:203], v[48:51]
	v_mfma_f32_16x16x32_bf16 v[44:47], v[156:159], v[200:203], v[44:47]
	v_mfma_f32_16x16x32_bf16 v[32:35], v[142:145], v[216:219], v[32:35]
	v_mfma_f32_16x16x32_bf16 v[28:31], v[156:159], v[216:219], v[28:31]
	v_mfma_f32_16x16x32_bf16 v[16:19], v[142:145], v[224:227], v[16:19]
	v_mfma_f32_16x16x32_bf16 v[12:15], v[156:159], v[224:227], v[12:15]
	v_mfma_f32_16x16x32_bf16 v[64:67], v[146:149], v[196:199], v[64:67]
	v_mfma_f32_16x16x32_bf16 v[60:63], v[172:175], v[196:199], v[60:63]
	v_mfma_f32_16x16x32_bf16 v[48:51], v[146:149], v[212:215], v[48:51]
	v_mfma_f32_16x16x32_bf16 v[44:47], v[172:175], v[212:215], v[44:47]
	v_mfma_f32_16x16x32_bf16 v[32:35], v[146:149], v[220:223], v[32:35]
	v_mfma_f32_16x16x32_bf16 v[28:31], v[172:175], v[220:223], v[28:31]
	v_mfma_f32_16x16x32_bf16 v[16:19], v[146:149], v[228:231], v[16:19]
	v_mfma_f32_16x16x32_bf16 v[12:15], v[172:175], v[228:231], v[12:15]
	s_setprio 0
	s_setprio 1
	v_mfma_f32_16x16x32_bf16 v[56:59], v[176:179], v[192:195], v[56:59]
	v_mfma_f32_16x16x32_bf16 v[52:55], v[184:187], v[192:195], v[52:55]
	v_mfma_f32_16x16x32_bf16 v[40:43], v[176:179], v[200:203], v[40:43]
	v_mfma_f32_16x16x32_bf16 v[36:39], v[184:187], v[200:203], v[36:39]
	v_mfma_f32_16x16x32_bf16 v[24:27], v[176:179], v[216:219], v[24:27]
	v_mfma_f32_16x16x32_bf16 v[20:23], v[184:187], v[216:219], v[20:23]
	v_mfma_f32_16x16x32_bf16 v[8:11], v[176:179], v[224:227], v[8:11]
	v_mfma_f32_16x16x32_bf16 v[4:7], v[184:187], v[224:227], v[4:7]
	v_mfma_f32_16x16x32_bf16 v[56:59], v[180:183], v[196:199], v[56:59]
	v_mfma_f32_16x16x32_bf16 v[52:55], v[188:191], v[196:199], v[52:55]
	v_mfma_f32_16x16x32_bf16 v[40:43], v[180:183], v[212:215], v[40:43]
	v_mfma_f32_16x16x32_bf16 v[36:39], v[188:191], v[212:215], v[36:39]
	v_mfma_f32_16x16x32_bf16 v[24:27], v[180:183], v[220:223], v[24:27]
	v_mfma_f32_16x16x32_bf16 v[20:23], v[188:191], v[220:223], v[20:23]
	v_mfma_f32_16x16x32_bf16 v[8:11], v[180:183], v[228:231], v[8:11]
	v_mfma_f32_16x16x32_bf16 v[4:7], v[188:191], v[228:231], v[4:7]
	s_setprio 0
	s_barrier
	s_add_i32 s54, s54, 2
	s_add_u32 s2, s2, 0x100
	s_addc_u32 s3, s3, 0
	s_cmp_gt_u32 s54, 29
	s_cbranch_scc0 .LBB0_174
	s_and_b64 vcc, exec, s[10:11]
	s_cbranch_vccz .LBB0_177
	s_barrier

; #define PG8_STAGE(bufoff, gbase, voff) do { _Pragma("unroll") for (int _i = 0; _i < 2; ++_i) \
;         __builtin_amdgcn_global_load_lds((const unsigned*)((const char*)(gbase) + (voff)[_i]), (PG8_LAS unsigned*)(lds + (bufoff) + ldsw + _i * 8192), 16, 0, 0); } while (0)
; #define PG8_LDA(dst, b, h) do { _Pragma("unroll") for (int m = 0; m < 4; ++m) _Pragma("unroll") for (int k = 0; k < 2; ++k) dst[m][k] = *(const PG8_LAS bf16x8*)(lds + PG8_SA(b, h) + aoff + m * 2048 + k * 1024); } while (0)
; #define PG8_LDB(dst, b, h) do { _Pragma("unroll") for (int n = 0; n < 2; ++n) _Pragma("unroll") for (int k = 0; k < 2; ++k) dst[n][k] = *(const PG8_LAS bf16x8*)(lds + PG8_SB(b, h) + boff + n * 2048 + k * 1024); } while (0)
; #define PG8_MMA(ai, bj, At, Bt) do { __builtin_amdgcn_s_setprio(1); _Pragma("unroll") for (int m = 0; m < 4; ++m) _Pragma("unroll") for (int n = 0; n < 2; ++n) _Pragma("unroll") for (int k = 0; k < 2; ++k) \
;         acc[ai][bj][m][n] = __builtin_amdgcn_mfma_f32_16x16x32_bf16(Bt[n][k], At[m][k], acc[ai][bj][m][n], 0, 0, 0); __builtin_amdgcn_s_setprio(0); } while (0)
; #define PG8_WAIT_V(n) asm volatile("s_waitcnt vmcnt(" #n ")" ::: "memory")
; #define PG8_WAIT_L(n) asm volatile("s_waitcnt lgkmcnt(" #n ")" ::: "memory")
; #define PG8_BAR __builtin_amdgcn_s_barrier()
; #define PG8_SCHED __builtin_amdgcn_sched_barrier(0)
; template <class Epi, class Sched, bool ALIGN_EPI = false, bool SP2 = false>
; __device__ __forceinline__ void gemm_phase(PG8_LAS unsigned char* lds, const Gemm g, const Sched& S, const Epi& E) {
;     ...
;             PG8_LDB(B0, 0, 0); PG8_LDB(B1, 0, 1); PG8_SCHED; PG8_LDA(At, 0, 0); PG8_STAGE(PG8_SA(1, 1), a1 + hstep, voffA);
;             PG8_WAIT_V(8); PG8_WAIT_L(0); PG8_BAR; PG8_MMA(0, 0, At, B0); PG8_MMA(0, 1, At, B1); PG8_BAR; PG8_SCHED;
;             PG8_LDA(At, 0, 1); PG8_STAGE(PG8_SB(0, 0), b2, voffB); PG8_STAGE(PG8_SB(0, 1), b2 + hstep, voffB); PG8_STAGE(PG8_SA(0, 0), a2, voffA);
;             PG8_WAIT_V(8); PG8_WAIT_L(0); PG8_BAR; PG8_MMA(1, 0, At, B0); PG8_MMA(1, 1, At, B1); PG8_BAR; PG8_SCHED;
.LBB0_926:
	s_add_u32 s2, s31, s46
	s_addc_u32 s3, s91, s47
	s_add_u32 s2, s2, 0x1ba00100
	s_addc_u32 s3, s3, 0
	s_add_u32 s67, s36, s46
	s_addc_u32 s68, s37, s47
	s_cmpk_eq_i32 s46, 0xf00
	s_cselect_b32 s49, s89, s3
	s_cselect_b32 s48, s88, s2
	s_cselect_b32 s3, s43, s68
	s_cselect_b32 s2, s61, s67
	s_add_i32 s67, 0, 0x10000
	v_add_u32_e32 v0, s67, v192
	s_add_i32 s70, 0, 0x14000
	ds_read_b128 v[132:135], v0
	ds_read_b128 v[136:139], v0 offset:1024
	ds_read_b128 v[140:143], v0 offset:2048
	ds_read_b128 v[144:147], v0 offset:3072
	v_add_u32_e32 v0, s70, v192
	ds_read_b128 v[148:151], v0
	ds_read_b128 v[152:155], v0 offset:1024
	ds_read_b128 v[180:183], v0 offset:2048
	ds_read_b128 v[184:187], v0 offset:3072
	v_lshl_add_u64 v[0:1], v[176:177], 0, s[46:47]
	s_add_i32 m0, s51, 0xc000
	ds_read_b128 v[188:191], v195
	ds_read_b128 v[196:199], v195 offset:1024
	ds_read_b128 v[200:203], v195 offset:2048
	ds_read_b128 v[212:215], v195 offset:3072
	ds_read_b128 v[216:219], v195 offset:4096
	ds_read_b128 v[220:223], v195 offset:5120
	ds_read_b128 v[224:227], v195 offset:6144
	ds_read_b128 v[228:231], v195 offset:7168
	global_load_lds_dwordx4 v[0:1], off
	v_lshl_add_u64 v[0:1], v[178:179], 0, s[46:47]
	s_add_i32 m0, s51, 0xe000
	s_nop 0
	global_load_lds_dwordx4 v[0:1], off
	s_waitcnt vmcnt(8)
	s_waitcnt lgkmcnt(0)
	s_barrier
	s_setprio 1
	s_waitcnt lgkmcnt(0)
	v_mfma_f32_16x16x32_bf16 v[128:131], v[132:135], v[188:191], v[128:131]
	v_mfma_f32_16x16x32_bf16 v[124:127], v[140:143], v[188:191], v[124:127]
	v_mfma_f32_16x16x32_bf16 v[112:115], v[132:135], v[200:203], v[112:115]
	v_mfma_f32_16x16x32_bf16 v[108:111], v[140:143], v[200:203], v[108:111]
	v_mfma_f32_16x16x32_bf16 v[96:99], v[132:135], v[216:219], v[96:99]
	v_mfma_f32_16x16x32_bf16 v[92:95], v[140:143], v[216:219], v[92:95]
	v_mfma_f32_16x16x32_bf16 v[80:83], v[132:135], v[224:227], v[80:83]
	v_mfma_f32_16x16x32_bf16 v[76:79], v[140:143], v[224:227], v[76:79]
	v_mfma_f32_16x16x32_bf16 v[128:131], v[136:139], v[196:199], v[128:131]
	v_mfma_f32_16x16x32_bf16 v[124:127], v[144:147], v[196:199], v[124:127]
	v_mfma_f32_16x16x32_bf16 v[112:115], v[136:139], v[212:215], v[112:115]
	v_mfma_f32_16x16x32_bf16 v[108:111], v[144:147], v[212:215], v[108:111]
	v_mfma_f32_16x16x32_bf16 v[96:99], v[136:139], v[220:223], v[96:99]
	v_mfma_f32_16x16x32_bf16 v[92:95], v[144:147], v[220:223], v[92:95]
	v_mfma_f32_16x16x32_bf16 v[80:83], v[136:139], v[228:231], v[80:83]
	v_mfma_f32_16x16x32_bf16 v[76:79], v[144:147], v[228:231], v[76:79]
	s_setprio 0
	s_setprio 1
	v_mfma_f32_16x16x32_bf16 v[120:123], v[148:151], v[188:191], v[120:123]
	v_mfma_f32_16x16x32_bf16 v[116:119], v[180:183], v[188:191], v[116:119]
	v_mfma_f32_16x16x32_bf16 v[104:107], v[148:151], v[200:203], v[104:107]
	v_mfma_f32_16x16x32_bf16 v[100:103], v[180:183], v[200:203], v[100:103]
	v_mfma_f32_16x16x32_bf16 v[88:91], v[148:151], v[216:219], v[88:91]
	v_mfma_f32_16x16x32_bf16 v[84:87], v[180:183], v[216:219], v[84:87]
	v_mfma_f32_16x16x32_bf16 v[72:75], v[148:151], v[224:227], v[72:75]
	v_mfma_f32_16x16x32_bf16 v[68:71], v[180:183], v[224:227], v[68:71]
	v_mfma_f32_16x16x32_bf16 v[120:123], v[152:155], v[196:199], v[120:123]
	v_mfma_f32_16x16x32_bf16 v[116:119], v[184:187], v[196:199], v[116:119]
	v_mfma_f32_16x16x32_bf16 v[104:107], v[152:155], v[212:215], v[104:107]
	v_mfma_f32_16x16x32_bf16 v[100:103], v[184:187], v[212:215], v[100:103]
	v_mfma_f32_16x16x32_bf16 v[88:91], v[152:155], v[220:223], v[88:91]
	v_mfma_f32_16x16x32_bf16 v[84:87], v[184:187], v[220:223], v[84:87]
	v_mfma_f32_16x16x32_bf16 v[72:75], v[152:155], v[228:231], v[72:75]
	v_mfma_f32_16x16x32_bf16 v[68:71], v[184:187], v[228:231], v[68:71]
	s_setprio 0
	s_barrier
	s_add_i32 s67, s67, s50
	s_add_u32 s98, s2, 0x80
	s_addc_u32 s99, s3, 0
	s_mov_b32 m0, s67
	ds_read_b128 v[188:191], v195 offset:16384
	ds_read_b128 v[196:199], v195 offset:17408
	ds_read_b128 v[200:203], v195 offset:18432
	ds_read_b128 v[212:215], v195 offset:19456
	ds_read_b128 v[216:219], v195 offset:20480
	ds_read_b128 v[220:223], v195 offset:21504
	ds_read_b128 v[224:227], v195 offset:22528
	ds_read_b128 v[228:231], v195 offset:23552
	global_load_lds_dwordx4 v172, s[2:3]
	s_add_i32 m0, s67, 0x2000
	s_add_u32 s68, s2, 0x80000
	s_addc_u32 s69, s3, 0
	s_add_i32 s67, s70, s50
	global_load_lds_dwordx4 v156, s[2:3]
	s_mov_b32 m0, s67
	s_add_u32 s100, s48, 0x80
	s_addc_u32 s101, s49, 0
	s_nop 0
	global_load_lds_dwordx4 v172, s[68:69]
	s_add_i32 m0, s67, 0x2000
	s_nop 0
	global_load_lds_dwordx4 v156, s[68:69]
	s_mov_b32 m0, s51
	s_nop 0
	global_load_lds_dwordx4 v174, s[48:49]
	s_mov_b32 m0, s54
	s_nop 0
	global_load_lds_dwordx4 v158, s[48:49]
	s_waitcnt vmcnt(8)
	s_waitcnt lgkmcnt(0)
	s_barrier
; #define PG8_STAGE(bufoff, gbase, voff) do { _Pragma("unroll") for (int _i = 0; _i < 2; ++_i) \
;         __builtin_amdgcn_global_load_lds((const unsigned*)((const char*)(gbase) + (voff)[_i]), (PG8_LAS unsigned*)(lds + (bufoff) + ldsw + _i * 8192), 16, 0, 0); } while (0)
; #define PG8_LDA(dst, b, h) do { _Pragma("unroll") for (int m = 0; m < 4; ++m) _Pragma("unroll") for (int k = 0; k < 2; ++k) dst[m][k] = *(const PG8_LAS bf16x8*)(lds + PG8_SA(b, h) + aoff + m * 2048 + k * 1024); } while (0)
; #define PG8_LDB(dst, b, h) do { _Pragma("unroll") for (int n = 0; n < 2; ++n) _Pragma("unroll") for (int k = 0; k < 2; ++k) dst[n][k] = *(const PG8_LAS bf16x8*)(lds + PG8_SB(b, h) + boff + n * 2048 + k * 1024); } while (0)
; #define PG8_MMA(ai, bj, At, Bt) do { __builtin_amdgcn_s_setprio(1); _Pragma("unroll") for (int m = 0; m < 4; ++m) _Pragma("unroll") for (int n = 0; n < 2; ++n) _Pragma("unroll") for (int k = 0; k < 2; ++k) \
;         acc[ai][bj][m][n] = __builtin_amdgcn_mfma_f32_16x16x32_bf16(Bt[n][k], At[m][k], acc[ai][bj][m][n], 0, 0, 0); __builtin_amdgcn_s_setprio(0); } while (0)
; #define PG8_WAIT_V(n) asm volatile("s_waitcnt vmcnt(" #n ")" ::: "memory")
; #define PG8_WAIT_L(n) asm volatile("s_waitcnt lgkmcnt(" #n ")" ::: "memory")
; #define PG8_BAR __builtin_amdgcn_s_barrier()
; #define PG8_SCHED __builtin_amdgcn_sched_barrier(0)
; template <class Epi, class Sched, bool ALIGN_EPI = false, bool SP2 = false>
; __device__ __forceinline__ void gemm_phase(PG8_LAS unsigned char* lds, const Gemm g, const Sched& S, const Epi& E) {
;     ...
;             PG8_WAIT_V(8); PG8_WAIT_L(0); PG8_BAR; PG8_MMA(1, 0, At, B0); PG8_MMA(1, 1, At, B1); PG8_BAR; PG8_SCHED;
;             PG8_LDB(B0, 1, 0); PG8_LDB(B1, 1, 1); PG8_SCHED; PG8_LDA(At, 1, 0); PG8_STAGE(PG8_SA(0, 1), a2 + hstep, voffA);
;             PG8_WAIT_V(8); PG8_WAIT_L(0); PG8_BAR; PG8_MMA(0, 0, At, B0); PG8_MMA(0, 1, At, B1); PG8_BAR; PG8_SCHED;
;             PG8_LDA(At, 1, 1); PG8_STAGE(PG8_SB(1, 0), b3, voffB); PG8_STAGE(PG8_SB(1, 1), b3 + hstep, voffB); PG8_STAGE(PG8_SA(1, 0), a3, voffA);
	s_setprio 1
	s_waitcnt lgkmcnt(0)
	v_mfma_f32_16x16x32_bf16 v[64:67], v[132:135], v[188:191], v[64:67]
	v_mfma_f32_16x16x32_bf16 v[60:63], v[140:143], v[188:191], v[60:63]
	v_mfma_f32_16x16x32_bf16 v[48:51], v[132:135], v[200:203], v[48:51]
	v_mfma_f32_16x16x32_bf16 v[44:47], v[140:143], v[200:203], v[44:47]
	v_mfma_f32_16x16x32_bf16 v[32:35], v[132:135], v[216:219], v[32:35]
	v_mfma_f32_16x16x32_bf16 v[28:31], v[140:143], v[216:219], v[28:31]
	v_mfma_f32_16x16x32_bf16 v[16:19], v[132:135], v[224:227], v[16:19]
	v_mfma_f32_16x16x32_bf16 v[12:15], v[140:143], v[224:227], v[12:15]
	v_mfma_f32_16x16x32_bf16 v[64:67], v[136:139], v[196:199], v[64:67]
	v_mfma_f32_16x16x32_bf16 v[60:63], v[144:147], v[196:199], v[60:63]
	v_mfma_f32_16x16x32_bf16 v[48:51], v[136:139], v[212:215], v[48:51]
	v_mfma_f32_16x16x32_bf16 v[44:47], v[144:147], v[212:215], v[44:47]
	v_mfma_f32_16x16x32_bf16 v[32:35], v[136:139], v[220:223], v[32:35]
	v_mfma_f32_16x16x32_bf16 v[28:31], v[144:147], v[220:223], v[28:31]
	v_mfma_f32_16x16x32_bf16 v[16:19], v[136:139], v[228:231], v[16:19]
	v_mfma_f32_16x16x32_bf16 v[12:15], v[144:147], v[228:231], v[12:15]
	s_setprio 0
	s_setprio 1
	v_mfma_f32_16x16x32_bf16 v[56:59], v[148:151], v[188:191], v[56:59]
	v_mfma_f32_16x16x32_bf16 v[52:55], v[180:183], v[188:191], v[52:55]
	v_mfma_f32_16x16x32_bf16 v[40:43], v[148:151], v[200:203], v[40:43]
	v_mfma_f32_16x16x32_bf16 v[36:39], v[180:183], v[200:203], v[36:39]
	v_mfma_f32_16x16x32_bf16 v[24:27], v[148:151], v[216:219], v[24:27]
	v_mfma_f32_16x16x32_bf16 v[20:23], v[180:183], v[216:219], v[20:23]
	v_mfma_f32_16x16x32_bf16 v[8:11], v[148:151], v[224:227], v[8:11]
	v_mfma_f32_16x16x32_bf16 v[4:7], v[180:183], v[224:227], v[4:7]
	v_mfma_f32_16x16x32_bf16 v[56:59], v[152:155], v[196:199], v[56:59]
	v_mfma_f32_16x16x32_bf16 v[52:55], v[184:187], v[196:199], v[52:55]
	v_mfma_f32_16x16x32_bf16 v[40:43], v[152:155], v[212:215], v[40:43]
	v_mfma_f32_16x16x32_bf16 v[36:39], v[184:187], v[212:215], v[36:39]
	v_mfma_f32_16x16x32_bf16 v[24:27], v[152:155], v[220:223], v[24:27]
	v_mfma_f32_16x16x32_bf16 v[20:23], v[184:187], v[220:223], v[20:23]
	v_mfma_f32_16x16x32_bf16 v[8:11], v[152:155], v[228:231], v[8:11]
	v_mfma_f32_16x16x32_bf16 v[4:7], v[184:187], v[228:231], v[4:7]
	s_setprio 0
	s_barrier
	s_add_i32 s67, 0, 0x18000
	v_add_u32_e32 v3, s67, v192
	s_add_i32 s68, 0, 0x1c000
	ds_read_b128 v[132:135], v3
	ds_read_b128 v[136:139], v3 offset:1024
	ds_read_b128 v[140:143], v3 offset:2048
	ds_read_b128 v[144:147], v3 offset:3072
	v_add_u32_e32 v3, s68, v192
	ds_read_b128 v[148:151], v3
	ds_read_b128 v[152:155], v3 offset:1024
	ds_read_b128 v[180:183], v3 offset:2048
	ds_read_b128 v[184:187], v3 offset:3072
	s_add_u32 s48, s48, 0x80000
	s_addc_u32 s49, s49, 0
	s_mov_b32 m0, s55
	ds_read_b128 v[188:191], v195 offset:32768
	ds_read_b128 v[196:199], v195 offset:33792
	ds_read_b128 v[200:203], v195 offset:34816
	ds_read_b128 v[212:215], v195 offset:35840
	ds_read_b128 v[216:219], v195 offset:36864
	ds_read_b128 v[220:223], v195 offset:37888
	ds_read_b128 v[224:227], v195 offset:38912
	ds_read_b128 v[228:231], v195 offset:39936
	global_load_lds_dwordx4 v174, s[48:49]
	s_mov_b32 m0, s56
	s_nop 0
	global_load_lds_dwordx4 v158, s[48:49]
	s_waitcnt vmcnt(8)
	s_waitcnt lgkmcnt(0)
	s_barrier
	s_setprio 1
	s_waitcnt lgkmcnt(0)
	v_mfma_f32_16x16x32_bf16 v[128:131], v[132:135], v[188:191], v[128:131]
	v_mfma_f32_16x16x32_bf16 v[124:127], v[140:143], v[188:191], v[124:127]
	v_mfma_f32_16x16x32_bf16 v[112:115], v[132:135], v[200:203], v[112:115]
	v_mfma_f32_16x16x32_bf16 v[108:111], v[140:143], v[200:203], v[108:111]
	v_mfma_f32_16x16x32_bf16 v[96:99], v[132:135], v[216:219], v[96:99]
	v_mfma_f32_16x16x32_bf16 v[92:95], v[140:143], v[216:219], v[92:95]
	v_mfma_f32_16x16x32_bf16 v[80:83], v[132:135], v[224:227], v[80:83]
	v_mfma_f32_16x16x32_bf16 v[76:79], v[140:143], v[224:227], v[76:79]
	v_mfma_f32_16x16x32_bf16 v[128:131], v[136:139], v[196:199], v[128:131]
	v_mfma_f32_16x16x32_bf16 v[124:127], v[144:147], v[196:199], v[124:127]
	v_mfma_f32_16x16x32_bf16 v[112:115], v[136:139], v[212:215], v[112:115]
	v_mfma_f32_16x16x32_bf16 v[108:111], v[144:147], v[212:215], v[108:111]
	v_mfma_f32_16x16x32_bf16 v[96:99], v[136:139], v[220:223], v[96:99]
	v_mfma_f32_16x16x32_bf16 v[92:95], v[144:147], v[220:223], v[92:95]
	v_mfma_f32_16x16x32_bf16 v[80:83], v[136:139], v[228:231], v[80:83]
	v_mfma_f32_16x16x32_bf16 v[76:79], v[144:147], v[228:231], v[76:79]
	s_setprio 0
	s_setprio 1
	v_mfma_f32_16x16x32_bf16 v[120:123], v[148:151], v[188:191], v[120:123]
	v_mfma_f32_16x16x32_bf16 v[116:119], v[180:183], v[188:191], v[116:119]
	v_mfma_f32_16x16x32_bf16 v[104:107], v[148:151], v[200:203], v[104:107]
	v_mfma_f32_16x16x32_bf16 v[100:103], v[180:183], v[200:203], v[100:103]
	v_mfma_f32_16x16x32_bf16 v[88:91], v[148:151], v[216:219], v[88:91]
	v_mfma_f32_16x16x32_bf16 v[84:87], v[180:183], v[216:219], v[84:87]
	v_mfma_f32_16x16x32_bf16 v[72:75], v[148:151], v[224:227], v[72:75]
	v_mfma_f32_16x16x32_bf16 v[68:71], v[180:183], v[224:227], v[68:71]
	v_mfma_f32_16x16x32_bf16 v[120:123], v[152:155], v[196:199], v[120:123]
	v_mfma_f32_16x16x32_bf16 v[116:119], v[184:187], v[196:199], v[116:119]
	v_mfma_f32_16x16x32_bf16 v[104:107], v[152:155], v[212:215], v[104:107]
	v_mfma_f32_16x16x32_bf16 v[100:103], v[184:187], v[212:215], v[100:103]
	v_mfma_f32_16x16x32_bf16 v[88:91], v[152:155], v[220:223], v[88:91]
	v_mfma_f32_16x16x32_bf16 v[84:87], v[184:187], v[220:223], v[84:87]
	v_mfma_f32_16x16x32_bf16 v[72:75], v[152:155], v[228:231], v[72:75]
	v_mfma_f32_16x16x32_bf16 v[68:71], v[184:187], v[228:231], v[68:71]
	s_setprio 0
	s_barrier
; #define PG8_STAGE(bufoff, gbase, voff) do { _Pragma("unroll") for (int _i = 0; _i < 2; ++_i) \
;         __builtin_amdgcn_global_load_lds((const unsigned*)((const char*)(gbase) + (voff)[_i]), (PG8_LAS unsigned*)(lds + (bufoff) + ldsw + _i * 8192), 16, 0, 0); } while (0)
; #define PG8_LDA(dst, b, h) do { _Pragma("unroll") for (int m = 0; m < 4; ++m) _Pragma("unroll") for (int k = 0; k < 2; ++k) dst[m][k] = *(const PG8_LAS bf16x8*)(lds + PG8_SA(b, h) + aoff + m * 2048 + k * 1024); } while (0)
; #define PG8_MMA(ai, bj, At, Bt) do { __builtin_amdgcn_s_setprio(1); _Pragma("unroll") for (int m = 0; m < 4; ++m) _Pragma("unroll") for (int n = 0; n < 2; ++n) _Pragma("unroll") for (int k = 0; k < 2; ++k) \
;         acc[ai][bj][m][n] = __builtin_amdgcn_mfma_f32_16x16x32_bf16(Bt[n][k], At[m][k], acc[ai][bj][m][n], 0, 0, 0); __builtin_amdgcn_s_setprio(0); } while (0)
; #define PG8_WAIT_V(n) asm volatile("s_waitcnt vmcnt(" #n ")" ::: "memory")
; #define PG8_WAIT_L(n) asm volatile("s_waitcnt lgkmcnt(" #n ")" ::: "memory")
; #define PG8_BAR __builtin_amdgcn_s_barrier()
; #define PG8_SCHED __builtin_amdgcn_sched_barrier(0)
; template <class Epi, class Sched, bool ALIGN_EPI = false, bool SP2 = false>
; __device__ __forceinline__ void gemm_phase(PG8_LAS unsigned char* lds, const Gemm g, const Sched& S, const Epi& E) {
;     ...
;             PG8_LDA(At, 1, 1); PG8_STAGE(PG8_SB(1, 0), b3, voffB); PG8_STAGE(PG8_SB(1, 1), b3 + hstep, voffB); PG8_STAGE(PG8_SA(1, 0), a3, voffA);
;             PG8_WAIT_V(8); PG8_WAIT_L(0); PG8_BAR; PG8_MMA(1, 0, At, B0); PG8_MMA(1, 1, At, B1); PG8_BAR; PG8_SCHED;
	s_add_i32 s48, s67, s50
	s_mov_b32 m0, s48
	ds_read_b128 v[188:191], v195 offset:49152
	ds_read_b128 v[196:199], v195 offset:50176
	ds_read_b128 v[200:203], v195 offset:51200
	ds_read_b128 v[212:215], v195 offset:52224
	ds_read_b128 v[216:219], v195 offset:53248
	ds_read_b128 v[220:223], v195 offset:54272
	ds_read_b128 v[224:227], v195 offset:55296
	ds_read_b128 v[228:231], v195 offset:56320
	global_load_lds_dwordx4 v172, s[98:99]
	s_add_i32 m0, s48, 0x2000
	s_add_u32 s2, s2, 0x80080
	s_addc_u32 s3, s3, 0
	s_add_i32 s48, s68, s50
	global_load_lds_dwordx4 v156, s[98:99]
	s_mov_b32 m0, s48
	s_nop 0
	global_load_lds_dwordx4 v172, s[2:3]
	s_add_i32 m0, s48, 0x2000
	s_nop 0
	global_load_lds_dwordx4 v156, s[2:3]
	s_mov_b32 m0, s57
	s_nop 0
	global_load_lds_dwordx4 v174, s[100:101]
	s_mov_b32 m0, s58
	s_nop 0
	global_load_lds_dwordx4 v158, s[100:101]
	s_waitcnt vmcnt(8)
	s_waitcnt lgkmcnt(0)
	s_barrier
	s_setprio 1
	s_waitcnt lgkmcnt(0)
	v_mfma_f32_16x16x32_bf16 v[64:67], v[132:135], v[188:191], v[64:67]
	v_mfma_f32_16x16x32_bf16 v[60:63], v[140:143], v[188:191], v[60:63]
	v_mfma_f32_16x16x32_bf16 v[48:51], v[132:135], v[200:203], v[48:51]
	v_mfma_f32_16x16x32_bf16 v[44:47], v[140:143], v[200:203], v[44:47]
	v_mfma_f32_16x16x32_bf16 v[32:35], v[132:135], v[216:219], v[32:35]
	v_mfma_f32_16x16x32_bf16 v[28:31], v[140:143], v[216:219], v[28:31]
	v_mfma_f32_16x16x32_bf16 v[16:19], v[132:135], v[224:227], v[16:19]
	v_mfma_f32_16x16x32_bf16 v[12:15], v[140:143], v[224:227], v[12:15]
	v_mfma_f32_16x16x32_bf16 v[64:67], v[136:139], v[196:199], v[64:67]
	v_mfma_f32_16x16x32_bf16 v[60:63], v[144:147], v[196:199], v[60:63]
	v_mfma_f32_16x16x32_bf16 v[48:51], v[136:139], v[212:215], v[48:51]
	v_mfma_f32_16x16x32_bf16 v[44:47], v[144:147], v[212:215], v[44:47]
	v_mfma_f32_16x16x32_bf16 v[32:35], v[136:139], v[220:223], v[32:35]
	v_mfma_f32_16x16x32_bf16 v[28:31], v[144:147], v[220:223], v[28:31]
	v_mfma_f32_16x16x32_bf16 v[16:19], v[136:139], v[228:231], v[16:19]
	v_mfma_f32_16x16x32_bf16 v[12:15], v[144:147], v[228:231], v[12:15]
	s_setprio 0
	s_setprio 1
	v_mfma_f32_16x16x32_bf16 v[56:59], v[148:151], v[188:191], v[56:59]
	v_mfma_f32_16x16x32_bf16 v[52:55], v[180:183], v[188:191], v[52:55]
	v_mfma_f32_16x16x32_bf16 v[40:43], v[148:151], v[200:203], v[40:43]
	v_mfma_f32_16x16x32_bf16 v[36:39], v[180:183], v[200:203], v[36:39]
	v_mfma_f32_16x16x32_bf16 v[24:27], v[148:151], v[216:219], v[24:27]
	v_mfma_f32_16x16x32_bf16 v[20:23], v[180:183], v[216:219], v[20:23]
	v_mfma_f32_16x16x32_bf16 v[8:11], v[148:151], v[224:227], v[8:11]
	v_mfma_f32_16x16x32_bf16 v[4:7], v[180:183], v[224:227], v[4:7]
	v_mfma_f32_16x16x32_bf16 v[56:59], v[152:155], v[196:199], v[56:59]
	v_mfma_f32_16x16x32_bf16 v[52:55], v[184:187], v[196:199], v[52:55]
	v_mfma_f32_16x16x32_bf16 v[40:43], v[152:155], v[212:215], v[40:43]
	v_mfma_f32_16x16x32_bf16 v[36:39], v[184:187], v[212:215], v[36:39]
	v_mfma_f32_16x16x32_bf16 v[24:27], v[152:155], v[220:223], v[24:27]
	v_mfma_f32_16x16x32_bf16 v[20:23], v[184:187], v[220:223], v[20:23]
	v_mfma_f32_16x16x32_bf16 v[8:11], v[152:155], v[228:231], v[8:11]
	v_mfma_f32_16x16x32_bf16 v[4:7], v[184:187], v[228:231], v[4:7]
	s_setprio 0
	s_barrier
	s_add_i32 s66, s66, 2
	s_add_u32 s46, s46, 0x100
	s_addc_u32 s47, s47, 0
	s_cmp_gt_u32 s66, 29
	s_cbranch_scc1 .LBB0_929

; #define PG8_STAGE(bufoff, gbase, voff) do { _Pragma("unroll") for (int _i = 0; _i < 2; ++_i) \
;         __builtin_amdgcn_global_load_lds((const unsigned*)((const char*)(gbase) + (voff)[_i]), (PG8_LAS unsigned*)(lds + (bufoff) + ldsw + _i * 8192), 16, 0, 0); } while (0)
; #define PG8_LDA(dst, b, h) do { _Pragma("unroll") for (int m = 0; m < 4; ++m) _Pragma("unroll") for (int k = 0; k < 2; ++k) dst[m][k] = *(const PG8_LAS bf16x8*)(lds + PG8_SA(b, h) + aoff + m * 2048 + k * 1024); } while (0)
; #define PG8_LDB(dst, b, h) do { _Pragma("unroll") for (int n = 0; n < 2; ++n) _Pragma("unroll") for (int k = 0; k < 2; ++k) dst[n][k] = *(const PG8_LAS bf16x8*)(lds + PG8_SB(b, h) + boff + n * 2048 + k * 1024); } while (0)
; #define PG8_MMA(ai, bj, At, Bt) do { __builtin_amdgcn_s_setprio(1); _Pragma("unroll") for (int m = 0; m < 4; ++m) _Pragma("unroll") for (int n = 0; n < 2; ++n) _Pragma("unroll") for (int k = 0; k < 2; ++k) \
;         acc[ai][bj][m][n] = __builtin_amdgcn_mfma_f32_16x16x32_bf16(Bt[n][k], At[m][k], acc[ai][bj][m][n], 0, 0, 0); __builtin_amdgcn_s_setprio(0); } while (0)
; #define PG8_WAIT_V(n) asm volatile("s_waitcnt vmcnt(" #n ")" ::: "memory")
; #define PG8_WAIT_L(n) asm volatile("s_waitcnt lgkmcnt(" #n ")" ::: "memory")
; #define PG8_BAR __builtin_amdgcn_s_barrier()
; #define PG8_SCHED __builtin_amdgcn_sched_barrier(0)
; template <class Epi, class Sched, bool ALIGN_EPI = false, bool SP2 = false>
; __device__ __forceinline__ void gemm_phase(PG8_LAS unsigned char* lds, const Gemm g, const Sched& S, const Epi& E) {
;     ...
;             PG8_LDB(B0, 0, 0); PG8_LDB(B1, 0, 1); PG8_SCHED; PG8_LDA(At, 0, 0); PG8_STAGE(PG8_SA(1, 1), a1 + hstep, voffA);
;             PG8_WAIT_V(8); PG8_WAIT_L(0); PG8_BAR; PG8_MMA(0, 0, At, B0); PG8_MMA(0, 1, At, B1); PG8_BAR; PG8_SCHED;
;     ...
; #pragma unroll
;         for (int a = 0; a < 2; ++a)
; #pragma unroll
;             for (int b = 0; b < 2; ++b)
; #pragma unroll
;                 for (int m = 0; m < 4; ++m)
; #pragma unroll
;                     for (int n = 0; n < 2; ++n) acc[a][b][m][n] = (f32x4){0.f, 0.f, 0.f, 0.f};
;         cur = nxt; cA = nA; cB = nB; ++ui;
.LBB0_1050:
	s_mov_b64 s[2:3], s[6:7]
	s_mov_b32 s6, s51
	s_add_i32 s51, s51, 1
	s_sub_i32 s7, 3, s6
	s_cmp_lt_u32 s6, 4
	s_cselect_b32 s6, s7, s51
	s_mov_b32 s52, s12
	s_lshl_b32 s6, s6, 3
	v_readlane_b32 s12, v248, 25
	s_add_i32 s12, s6, s12
	v_readlane_b32 s13, v248, 26
	s_cmp_lt_i32 s12, 44
	s_cselect_b64 s[14:15], -1, 0
	s_ashr_i32 s13, s12, 31
	s_lshl_b64 s[6:7], s[12:13], 20
	s_add_u32 s6, s46, s6
	s_addc_u32 s7, s47, s7
	s_and_b64 s[36:37], s[14:15], exec
	s_cselect_b32 s13, s7, s3
	s_cselect_b32 s53, s6, s2
	s_add_u32 s54, s2, 0x100
	v_mov_b32_e32 v12, 0
	s_addc_u32 s55, s3, 0
	s_mov_b32 s56, -2
	s_mov_b64 s[2:3], 0
	v_mov_b32_e32 v13, v12
	v_mov_b32_e32 v14, v12
	v_mov_b32_e32 v15, v12
	v_mov_b32_e32 v16, v12
	v_mov_b32_e32 v17, v12
	v_mov_b32_e32 v18, v12
	v_mov_b32_e32 v19, v12
	v_mov_b32_e32 v28, v12
	v_mov_b32_e32 v29, v12
	v_mov_b32_e32 v30, v12
	v_mov_b32_e32 v31, v12
	v_mov_b32_e32 v32, v12
	v_mov_b32_e32 v33, v12
	v_mov_b32_e32 v34, v12
	v_mov_b32_e32 v35, v12
	v_mov_b32_e32 v44, v12
	v_mov_b32_e32 v45, v12
	v_mov_b32_e32 v46, v12
	v_mov_b32_e32 v47, v12
	v_mov_b32_e32 v48, v12
	v_mov_b32_e32 v49, v12
	v_mov_b32_e32 v50, v12
	v_mov_b32_e32 v51, v12
	v_mov_b32_e32 v60, v12
	v_mov_b32_e32 v61, v12
	v_mov_b32_e32 v62, v12
	v_mov_b32_e32 v63, v12
	v_mov_b32_e32 v64, v12
	v_mov_b32_e32 v65, v12
	v_mov_b32_e32 v66, v12
	v_mov_b32_e32 v67, v12
	v_mov_b32_e32 v4, v12
	v_mov_b32_e32 v5, v12
	v_mov_b32_e32 v6, v12
	v_mov_b32_e32 v7, v12
	v_mov_b32_e32 v8, v12
	v_mov_b32_e32 v9, v12
	v_mov_b32_e32 v10, v12
	v_mov_b32_e32 v11, v12
	v_mov_b32_e32 v20, v12
	v_mov_b32_e32 v21, v12
	v_mov_b32_e32 v22, v12
	v_mov_b32_e32 v23, v12
	v_mov_b32_e32 v24, v12
	v_mov_b32_e32 v25, v12
	v_mov_b32_e32 v26, v12
	v_mov_b32_e32 v27, v12
	v_mov_b32_e32 v36, v12
	v_mov_b32_e32 v37, v12
	v_mov_b32_e32 v38, v12
	v_mov_b32_e32 v39, v12
	v_mov_b32_e32 v40, v12
	v_mov_b32_e32 v41, v12
	v_mov_b32_e32 v42, v12
	v_mov_b32_e32 v43, v12
	v_mov_b32_e32 v52, v12
	v_mov_b32_e32 v53, v12
	v_mov_b32_e32 v54, v12
	v_mov_b32_e32 v55, v12
	v_mov_b32_e32 v56, v12
	v_mov_b32_e32 v57, v12
	v_mov_b32_e32 v58, v12
	v_mov_b32_e32 v59, v12
	v_mov_b32_e32 v76, v12
	v_mov_b32_e32 v77, v12
	v_mov_b32_e32 v78, v12
	v_mov_b32_e32 v79, v12
	v_mov_b32_e32 v80, v12
	v_mov_b32_e32 v81, v12
	v_mov_b32_e32 v82, v12
	v_mov_b32_e32 v83, v12
	v_mov_b32_e32 v92, v12
	v_mov_b32_e32 v93, v12
	v_mov_b32_e32 v94, v12
	v_mov_b32_e32 v95, v12
	v_mov_b32_e32 v96, v12
	v_mov_b32_e32 v97, v12
	v_mov_b32_e32 v98, v12
	v_mov_b32_e32 v99, v12
	v_mov_b32_e32 v108, v12
	v_mov_b32_e32 v109, v12
	v_mov_b32_e32 v110, v12
	v_mov_b32_e32 v111, v12
	v_mov_b32_e32 v112, v12
	v_mov_b32_e32 v113, v12
	v_mov_b32_e32 v114, v12
	v_mov_b32_e32 v115, v12
	v_mov_b32_e32 v124, v12
	v_mov_b32_e32 v125, v12
	v_mov_b32_e32 v126, v12
	v_mov_b32_e32 v127, v12
	v_mov_b32_e32 v128, v12
	v_mov_b32_e32 v129, v12
	v_mov_b32_e32 v130, v12
	v_mov_b32_e32 v131, v12
	v_mov_b32_e32 v68, v12
	v_mov_b32_e32 v69, v12
	v_mov_b32_e32 v70, v12
	v_mov_b32_e32 v71, v12
	v_mov_b32_e32 v72, v12
	v_mov_b32_e32 v73, v12
	v_mov_b32_e32 v74, v12
	v_mov_b32_e32 v75, v12
	v_mov_b32_e32 v84, v12
	v_mov_b32_e32 v85, v12
	v_mov_b32_e32 v86, v12
	v_mov_b32_e32 v87, v12
	v_mov_b32_e32 v88, v12
	v_mov_b32_e32 v89, v12
	v_mov_b32_e32 v90, v12
	v_mov_b32_e32 v91, v12
	v_mov_b32_e32 v100, v12
	v_mov_b32_e32 v101, v12
	v_mov_b32_e32 v102, v12
	v_mov_b32_e32 v103, v12
	v_mov_b32_e32 v104, v12
	v_mov_b32_e32 v105, v12
	v_mov_b32_e32 v106, v12
	v_mov_b32_e32 v107, v12
	v_mov_b32_e32 v116, v12
	v_mov_b32_e32 v117, v12
	v_mov_b32_e32 v118, v12
	v_mov_b32_e32 v119, v12
	v_mov_b32_e32 v120, v12
	v_mov_b32_e32 v121, v12
	v_mov_b32_e32 v122, v12
	v_mov_b32_e32 v123, v12
	v_add_u32_e32 v168, 0x10000, v3
	v_add_u32_e32 v169, 0x14000, v3
	v_add_u32_e32 v170, 0x18000, v3
	v_add_u32_e32 v171, 0x1c000, v3
.LBB0_1051:
	s_add_u32 s36, s31, s2
	s_addc_u32 s37, s91, s3
	s_add_u32 s36, s36, 0x16200100
	s_addc_u32 s37, s37, 0
	s_add_u32 s57, s54, s2
	s_addc_u32 s58, s55, s3
	s_add_i32 s59, 0, 0x10000
	s_cmpk_eq_i32 s2, 0xf00
	s_cselect_b32 s41, s1, s37
	s_cselect_b32 s40, s0, s36
	s_cselect_b32 s37, s13, s58
	s_cselect_b32 s36, s53, s57
	s_add_i32 s57, 0, 0x14000
	ds_read_b128 v[142:145], v168
	ds_read_b128 v[152:155], v168 offset:1024
	ds_read_b128 v[156:159], v168 offset:2048
	ds_read_b128 v[172:175], v168 offset:3072
	ds_read_b128 v[176:179], v169
	ds_read_b128 v[180:183], v169 offset:1024
	ds_read_b128 v[184:187], v169 offset:2048
	ds_read_b128 v[188:191], v169 offset:3072
	v_lshl_add_u64 v[146:147], v[138:139], 0, s[2:3]
	s_add_i32 m0, s43, 0xc000
	ds_read_b128 v[192:195], v150
	ds_read_b128 v[196:199], v150 offset:1024
	ds_read_b128 v[200:203], v150 offset:2048
	ds_read_b128 v[212:215], v150 offset:3072
	ds_read_b128 v[216:219], v150 offset:4096
	ds_read_b128 v[220:223], v150 offset:5120
	ds_read_b128 v[224:227], v150 offset:6144
	ds_read_b128 v[228:231], v150 offset:7168
	global_load_lds_dwordx4 v[146:147], off
	v_lshl_add_u64 v[146:147], v[140:141], 0, s[2:3]
	s_add_i32 m0, s43, 0xe000
	s_nop 0
	global_load_lds_dwordx4 v[146:147], off
	s_waitcnt vmcnt(8)
	s_waitcnt lgkmcnt(0)
	s_barrier
; #define PG8_STAGE(bufoff, gbase, voff) do { _Pragma("unroll") for (int _i = 0; _i < 2; ++_i) \
;         __builtin_amdgcn_global_load_lds((const unsigned*)((const char*)(gbase) + (voff)[_i]), (PG8_LAS unsigned*)(lds + (bufoff) + ldsw + _i * 8192), 16, 0, 0); } while (0)
; #define PG8_LDA(dst, b, h) do { _Pragma("unroll") for (int m = 0; m < 4; ++m) _Pragma("unroll") for (int k = 0; k < 2; ++k) dst[m][k] = *(const PG8_LAS bf16x8*)(lds + PG8_SA(b, h) + aoff + m * 2048 + k * 1024); } while (0)
; #define PG8_LDB(dst, b, h) do { _Pragma("unroll") for (int n = 0; n < 2; ++n) _Pragma("unroll") for (int k = 0; k < 2; ++k) dst[n][k] = *(const PG8_LAS bf16x8*)(lds + PG8_SB(b, h) + boff + n * 2048 + k * 1024); } while (0)
; #define PG8_MMA(ai, bj, At, Bt) do { __builtin_amdgcn_s_setprio(1); _Pragma("unroll") for (int m = 0; m < 4; ++m) _Pragma("unroll") for (int n = 0; n < 2; ++n) _Pragma("unroll") for (int k = 0; k < 2; ++k) \
;         acc[ai][bj][m][n] = __builtin_amdgcn_mfma_f32_16x16x32_bf16(Bt[n][k], At[m][k], acc[ai][bj][m][n], 0, 0, 0); __builtin_amdgcn_s_setprio(0); } while (0)
; #define PG8_WAIT_V(n) asm volatile("s_waitcnt vmcnt(" #n ")" ::: "memory")
; #define PG8_WAIT_L(n) asm volatile("s_waitcnt lgkmcnt(" #n ")" ::: "memory")
; #define PG8_BAR __builtin_amdgcn_s_barrier()
; #define PG8_SCHED __builtin_amdgcn_sched_barrier(0)
; template <class Epi, class Sched, bool ALIGN_EPI = false, bool SP2 = false>
; __device__ __forceinline__ void gemm_phase(PG8_LAS unsigned char* lds, const Gemm g, const Sched& S, const Epi& E) {
;     ...
;             PG8_LDB(B0, 0, 0); PG8_LDB(B1, 0, 1); PG8_SCHED; PG8_LDA(At, 0, 0); PG8_STAGE(PG8_SA(1, 1), a1 + hstep, voffA);
;             PG8_WAIT_V(8); PG8_WAIT_L(0); PG8_BAR; PG8_MMA(0, 0, At, B0); PG8_MMA(0, 1, At, B1); PG8_BAR; PG8_SCHED;
;             PG8_LDA(At, 0, 1); PG8_STAGE(PG8_SB(0, 0), b2, voffB); PG8_STAGE(PG8_SB(0, 1), b2 + hstep, voffB); PG8_STAGE(PG8_SA(0, 0), a2, voffA);
;             PG8_WAIT_V(8); PG8_WAIT_L(0); PG8_BAR; PG8_MMA(1, 0, At, B0); PG8_MMA(1, 1, At, B1); PG8_BAR; PG8_SCHED;
	s_setprio 1
	s_waitcnt lgkmcnt(0)
	v_mfma_f32_16x16x32_bf16 v[120:123], v[142:145], v[192:195], v[120:123]
	v_mfma_f32_16x16x32_bf16 v[116:119], v[156:159], v[192:195], v[116:119]
	v_mfma_f32_16x16x32_bf16 v[104:107], v[142:145], v[200:203], v[104:107]
	v_mfma_f32_16x16x32_bf16 v[100:103], v[156:159], v[200:203], v[100:103]
	v_mfma_f32_16x16x32_bf16 v[88:91], v[142:145], v[216:219], v[88:91]
	v_mfma_f32_16x16x32_bf16 v[84:87], v[156:159], v[216:219], v[84:87]
	v_mfma_f32_16x16x32_bf16 v[72:75], v[142:145], v[224:227], v[72:75]
	v_mfma_f32_16x16x32_bf16 v[68:71], v[156:159], v[224:227], v[68:71]
	v_mfma_f32_16x16x32_bf16 v[120:123], v[152:155], v[196:199], v[120:123]
	v_mfma_f32_16x16x32_bf16 v[116:119], v[172:175], v[196:199], v[116:119]
	v_mfma_f32_16x16x32_bf16 v[104:107], v[152:155], v[212:215], v[104:107]
	v_mfma_f32_16x16x32_bf16 v[100:103], v[172:175], v[212:215], v[100:103]
	v_mfma_f32_16x16x32_bf16 v[88:91], v[152:155], v[220:223], v[88:91]
	v_mfma_f32_16x16x32_bf16 v[84:87], v[172:175], v[220:223], v[84:87]
	v_mfma_f32_16x16x32_bf16 v[72:75], v[152:155], v[228:231], v[72:75]
	v_mfma_f32_16x16x32_bf16 v[68:71], v[172:175], v[228:231], v[68:71]
	s_setprio 0
	s_setprio 1
	v_mfma_f32_16x16x32_bf16 v[128:131], v[176:179], v[192:195], v[128:131]
	v_mfma_f32_16x16x32_bf16 v[124:127], v[184:187], v[192:195], v[124:127]
	v_mfma_f32_16x16x32_bf16 v[112:115], v[176:179], v[200:203], v[112:115]
	v_mfma_f32_16x16x32_bf16 v[108:111], v[184:187], v[200:203], v[108:111]
	v_mfma_f32_16x16x32_bf16 v[96:99], v[176:179], v[216:219], v[96:99]
	v_mfma_f32_16x16x32_bf16 v[92:95], v[184:187], v[216:219], v[92:95]
	v_mfma_f32_16x16x32_bf16 v[80:83], v[176:179], v[224:227], v[80:83]
	v_mfma_f32_16x16x32_bf16 v[76:79], v[184:187], v[224:227], v[76:79]
	v_mfma_f32_16x16x32_bf16 v[128:131], v[180:183], v[196:199], v[128:131]
	v_mfma_f32_16x16x32_bf16 v[124:127], v[188:191], v[196:199], v[124:127]
	v_mfma_f32_16x16x32_bf16 v[112:115], v[180:183], v[212:215], v[112:115]
	v_mfma_f32_16x16x32_bf16 v[108:111], v[188:191], v[212:215], v[108:111]
	v_mfma_f32_16x16x32_bf16 v[96:99], v[180:183], v[220:223], v[96:99]
	v_mfma_f32_16x16x32_bf16 v[92:95], v[188:191], v[220:223], v[92:95]
	v_mfma_f32_16x16x32_bf16 v[80:83], v[180:183], v[228:231], v[80:83]
	v_mfma_f32_16x16x32_bf16 v[76:79], v[188:191], v[228:231], v[76:79]
	s_setprio 0
	s_barrier
	s_add_i32 s58, s59, s42
	s_add_u32 s98, s36, 0x80
	s_addc_u32 s99, s37, 0
	s_mov_b32 m0, s58
	ds_read_b128 v[192:195], v150 offset:16384
	ds_read_b128 v[196:199], v150 offset:17408
	ds_read_b128 v[200:203], v150 offset:18432
	ds_read_b128 v[212:215], v150 offset:19456
	ds_read_b128 v[216:219], v150 offset:20480
	ds_read_b128 v[220:223], v150 offset:21504
	ds_read_b128 v[224:227], v150 offset:22528
	ds_read_b128 v[228:231], v150 offset:23552
	global_load_lds_dwordx4 v134, s[36:37]
	s_add_i32 m0, s58, 0x2000
	s_add_u32 s58, s36, 0x80000
	s_addc_u32 s59, s37, 0
	s_add_i32 s57, s57, s42
	global_load_lds_dwordx4 v0, s[36:37]
	s_mov_b32 m0, s57
	s_add_u32 s100, s40, 0x80
	s_addc_u32 s101, s41, 0
	s_nop 0
	global_load_lds_dwordx4 v134, s[58:59]
	s_add_i32 m0, s57, 0x2000
	s_nop 0
	global_load_lds_dwordx4 v0, s[58:59]
	s_mov_b32 m0, s43
	s_nop 0
	global_load_lds_dwordx4 v136, s[40:41]
	s_mov_b32 m0, s44
	s_nop 0
	global_load_lds_dwordx4 v132, s[40:41]
	s_waitcnt vmcnt(8)
	s_waitcnt lgkmcnt(0)
	s_barrier
	s_setprio 1
	s_waitcnt lgkmcnt(0)
	v_mfma_f32_16x16x32_bf16 v[56:59], v[142:145], v[192:195], v[56:59]
	v_mfma_f32_16x16x32_bf16 v[52:55], v[156:159], v[192:195], v[52:55]
	v_mfma_f32_16x16x32_bf16 v[40:43], v[142:145], v[200:203], v[40:43]
	v_mfma_f32_16x16x32_bf16 v[36:39], v[156:159], v[200:203], v[36:39]
	v_mfma_f32_16x16x32_bf16 v[24:27], v[142:145], v[216:219], v[24:27]
	v_mfma_f32_16x16x32_bf16 v[20:23], v[156:159], v[216:219], v[20:23]
	v_mfma_f32_16x16x32_bf16 v[8:11], v[142:145], v[224:227], v[8:11]
	v_mfma_f32_16x16x32_bf16 v[4:7], v[156:159], v[224:227], v[4:7]
	v_mfma_f32_16x16x32_bf16 v[56:59], v[152:155], v[196:199], v[56:59]
	v_mfma_f32_16x16x32_bf16 v[52:55], v[172:175], v[196:199], v[52:55]
	v_mfma_f32_16x16x32_bf16 v[40:43], v[152:155], v[212:215], v[40:43]
	v_mfma_f32_16x16x32_bf16 v[36:39], v[172:175], v[212:215], v[36:39]
	v_mfma_f32_16x16x32_bf16 v[24:27], v[152:155], v[220:223], v[24:27]
	v_mfma_f32_16x16x32_bf16 v[20:23], v[172:175], v[220:223], v[20:23]
	v_mfma_f32_16x16x32_bf16 v[8:11], v[152:155], v[228:231], v[8:11]
	v_mfma_f32_16x16x32_bf16 v[4:7], v[172:175], v[228:231], v[4:7]
	s_setprio 0
	s_setprio 1
	v_mfma_f32_16x16x32_bf16 v[64:67], v[176:179], v[192:195], v[64:67]
	v_mfma_f32_16x16x32_bf16 v[60:63], v[184:187], v[192:195], v[60:63]
	v_mfma_f32_16x16x32_bf16 v[48:51], v[176:179], v[200:203], v[48:51]
	v_mfma_f32_16x16x32_bf16 v[44:47], v[184:187], v[200:203], v[44:47]
	v_mfma_f32_16x16x32_bf16 v[32:35], v[176:179], v[216:219], v[32:35]
	v_mfma_f32_16x16x32_bf16 v[28:31], v[184:187], v[216:219], v[28:31]
	v_mfma_f32_16x16x32_bf16 v[16:19], v[176:179], v[224:227], v[16:19]
	v_mfma_f32_16x16x32_bf16 v[12:15], v[184:187], v[224:227], v[12:15]
	v_mfma_f32_16x16x32_bf16 v[64:67], v[180:183], v[196:199], v[64:67]
	v_mfma_f32_16x16x32_bf16 v[60:63], v[188:191], v[196:199], v[60:63]
	v_mfma_f32_16x16x32_bf16 v[48:51], v[180:183], v[212:215], v[48:51]
	v_mfma_f32_16x16x32_bf16 v[44:47], v[188:191], v[212:215], v[44:47]
	v_mfma_f32_16x16x32_bf16 v[32:35], v[180:183], v[220:223], v[32:35]
	v_mfma_f32_16x16x32_bf16 v[28:31], v[188:191], v[220:223], v[28:31]
	v_mfma_f32_16x16x32_bf16 v[16:19], v[180:183], v[228:231], v[16:19]
	v_mfma_f32_16x16x32_bf16 v[12:15], v[188:191], v[228:231], v[12:15]
	s_setprio 0
	s_barrier
; #define PG8_STAGE(bufoff, gbase, voff) do { _Pragma("unroll") for (int _i = 0; _i < 2; ++_i) \
;         __builtin_amdgcn_global_load_lds((const unsigned*)((const char*)(gbase) + (voff)[_i]), (PG8_LAS unsigned*)(lds + (bufoff) + ldsw + _i * 8192), 16, 0, 0); } while (0)
; #define PG8_LDA(dst, b, h) do { _Pragma("unroll") for (int m = 0; m < 4; ++m) _Pragma("unroll") for (int k = 0; k < 2; ++k) dst[m][k] = *(const PG8_LAS bf16x8*)(lds + PG8_SA(b, h) + aoff + m * 2048 + k * 1024); } while (0)
; #define PG8_LDB(dst, b, h) do { _Pragma("unroll") for (int n = 0; n < 2; ++n) _Pragma("unroll") for (int k = 0; k < 2; ++k) dst[n][k] = *(const PG8_LAS bf16x8*)(lds + PG8_SB(b, h) + boff + n * 2048 + k * 1024); } while (0)
; #define PG8_MMA(ai, bj, At, Bt) do { __builtin_amdgcn_s_setprio(1); _Pragma("unroll") for (int m = 0; m < 4; ++m) _Pragma("unroll") for (int n = 0; n < 2; ++n) _Pragma("unroll") for (int k = 0; k < 2; ++k) \
;         acc[ai][bj][m][n] = __builtin_amdgcn_mfma_f32_16x16x32_bf16(Bt[n][k], At[m][k], acc[ai][bj][m][n], 0, 0, 0); __builtin_amdgcn_s_setprio(0); } while (0)
; #define PG8_WAIT_V(n) asm volatile("s_waitcnt vmcnt(" #n ")" ::: "memory")
; #define PG8_WAIT_L(n) asm volatile("s_waitcnt lgkmcnt(" #n ")" ::: "memory")
; #define PG8_BAR __builtin_amdgcn_s_barrier()
; #define PG8_SCHED __builtin_amdgcn_sched_barrier(0)
; template <class Epi, class Sched, bool ALIGN_EPI = false, bool SP2 = false>
; __device__ __forceinline__ void gemm_phase(PG8_LAS unsigned char* lds, const Gemm g, const Sched& S, const Epi& E) {
;     ...
;             PG8_WAIT_V(8); PG8_WAIT_L(0); PG8_BAR; PG8_MMA(1, 0, At, B0); PG8_MMA(1, 1, At, B1); PG8_BAR; PG8_SCHED;
;             PG8_LDB(B0, 1, 0); PG8_LDB(B1, 1, 1); PG8_SCHED; PG8_LDA(At, 1, 0); PG8_STAGE(PG8_SA(0, 1), a2 + hstep, voffA);
;             PG8_WAIT_V(8); PG8_WAIT_L(0); PG8_BAR; PG8_MMA(0, 0, At, B0); PG8_MMA(0, 1, At, B1); PG8_BAR; PG8_SCHED;
;             PG8_LDA(At, 1, 1); PG8_STAGE(PG8_SB(1, 0), b3, voffB); PG8_STAGE(PG8_SB(1, 1), b3 + hstep, voffB); PG8_STAGE(PG8_SA(1, 0), a3, voffA);
;             PG8_WAIT_V(8); PG8_WAIT_L(0); PG8_BAR; PG8_MMA(1, 0, At, B0); PG8_MMA(1, 1, At, B1); PG8_BAR; PG8_SCHED;
	s_add_i32 s57, 0, 0x18000
	s_add_i32 s58, 0, 0x1c000
	ds_read_b128 v[142:145], v170
	ds_read_b128 v[152:155], v170 offset:1024
	ds_read_b128 v[156:159], v170 offset:2048
	ds_read_b128 v[172:175], v170 offset:3072
	ds_read_b128 v[176:179], v171
	ds_read_b128 v[180:183], v171 offset:1024
	ds_read_b128 v[184:187], v171 offset:2048
	ds_read_b128 v[188:191], v171 offset:3072
	s_add_u32 s40, s40, 0x80000
	s_addc_u32 s41, s41, 0
	s_mov_b32 m0, s45
	ds_read_b128 v[192:195], v150 offset:32768
	ds_read_b128 v[196:199], v150 offset:33792
	ds_read_b128 v[200:203], v150 offset:34816
	ds_read_b128 v[212:215], v150 offset:35840
	ds_read_b128 v[216:219], v150 offset:36864
	ds_read_b128 v[220:223], v150 offset:37888
	ds_read_b128 v[224:227], v150 offset:38912
	ds_read_b128 v[228:231], v150 offset:39936
	global_load_lds_dwordx4 v136, s[40:41]
	s_mov_b32 m0, s48
	s_nop 0
	global_load_lds_dwordx4 v132, s[40:41]
	s_waitcnt vmcnt(8)
	s_waitcnt lgkmcnt(0)
	s_barrier
	s_setprio 1
	s_waitcnt lgkmcnt(0)
	v_mfma_f32_16x16x32_bf16 v[120:123], v[142:145], v[192:195], v[120:123]
	v_mfma_f32_16x16x32_bf16 v[116:119], v[156:159], v[192:195], v[116:119]
	v_mfma_f32_16x16x32_bf16 v[104:107], v[142:145], v[200:203], v[104:107]
	v_mfma_f32_16x16x32_bf16 v[100:103], v[156:159], v[200:203], v[100:103]
	v_mfma_f32_16x16x32_bf16 v[88:91], v[142:145], v[216:219], v[88:91]
	v_mfma_f32_16x16x32_bf16 v[84:87], v[156:159], v[216:219], v[84:87]
	v_mfma_f32_16x16x32_bf16 v[72:75], v[142:145], v[224:227], v[72:75]
	v_mfma_f32_16x16x32_bf16 v[68:71], v[156:159], v[224:227], v[68:71]
	v_mfma_f32_16x16x32_bf16 v[120:123], v[152:155], v[196:199], v[120:123]
	v_mfma_f32_16x16x32_bf16 v[116:119], v[172:175], v[196:199], v[116:119]
	v_mfma_f32_16x16x32_bf16 v[104:107], v[152:155], v[212:215], v[104:107]
	v_mfma_f32_16x16x32_bf16 v[100:103], v[172:175], v[212:215], v[100:103]
	v_mfma_f32_16x16x32_bf16 v[88:91], v[152:155], v[220:223], v[88:91]
	v_mfma_f32_16x16x32_bf16 v[84:87], v[172:175], v[220:223], v[84:87]
	v_mfma_f32_16x16x32_bf16 v[72:75], v[152:155], v[228:231], v[72:75]
	v_mfma_f32_16x16x32_bf16 v[68:71], v[172:175], v[228:231], v[68:71]
	s_setprio 0
	s_setprio 1
	v_mfma_f32_16x16x32_bf16 v[128:131], v[176:179], v[192:195], v[128:131]
	v_mfma_f32_16x16x32_bf16 v[124:127], v[184:187], v[192:195], v[124:127]
	v_mfma_f32_16x16x32_bf16 v[112:115], v[176:179], v[200:203], v[112:115]
	v_mfma_f32_16x16x32_bf16 v[108:111], v[184:187], v[200:203], v[108:111]
	v_mfma_f32_16x16x32_bf16 v[96:99], v[176:179], v[216:219], v[96:99]
	v_mfma_f32_16x16x32_bf16 v[92:95], v[184:187], v[216:219], v[92:95]
	v_mfma_f32_16x16x32_bf16 v[80:83], v[176:179], v[224:227], v[80:83]
	v_mfma_f32_16x16x32_bf16 v[76:79], v[184:187], v[224:227], v[76:79]
	v_mfma_f32_16x16x32_bf16 v[128:131], v[180:183], v[196:199], v[128:131]
	v_mfma_f32_16x16x32_bf16 v[124:127], v[188:191], v[196:199], v[124:127]
	v_mfma_f32_16x16x32_bf16 v[112:115], v[180:183], v[212:215], v[112:115]
	v_mfma_f32_16x16x32_bf16 v[108:111], v[188:191], v[212:215], v[108:111]
	v_mfma_f32_16x16x32_bf16 v[96:99], v[180:183], v[220:223], v[96:99]
	v_mfma_f32_16x16x32_bf16 v[92:95], v[188:191], v[220:223], v[92:95]
	v_mfma_f32_16x16x32_bf16 v[80:83], v[180:183], v[228:231], v[80:83]
	v_mfma_f32_16x16x32_bf16 v[76:79], v[188:191], v[228:231], v[76:79]
	s_setprio 0
	s_barrier
	s_add_i32 s40, s57, s42
	s_mov_b32 m0, s40
	ds_read_b128 v[192:195], v150 offset:49152
	ds_read_b128 v[196:199], v150 offset:50176
	ds_read_b128 v[200:203], v150 offset:51200
	ds_read_b128 v[212:215], v150 offset:52224
	ds_read_b128 v[216:219], v150 offset:53248
	ds_read_b128 v[220:223], v150 offset:54272
	ds_read_b128 v[224:227], v150 offset:55296
	ds_read_b128 v[228:231], v150 offset:56320
	global_load_lds_dwordx4 v134, s[98:99]
	s_add_i32 m0, s40, 0x2000
	s_add_u32 s36, s36, 0x80080
	s_addc_u32 s37, s37, 0
	s_add_i32 s40, s58, s42
	global_load_lds_dwordx4 v0, s[98:99]
	s_mov_b32 m0, s40
	s_nop 0
	global_load_lds_dwordx4 v134, s[36:37]
	s_add_i32 m0, s40, 0x2000
	s_nop 0
	global_load_lds_dwordx4 v0, s[36:37]
	s_mov_b32 m0, s49
	s_nop 0
	global_load_lds_dwordx4 v136, s[100:101]
	s_mov_b32 m0, s50
	s_nop 0
	global_load_lds_dwordx4 v132, s[100:101]
	s_waitcnt vmcnt(8)
	s_waitcnt lgkmcnt(0)
	s_barrier
	s_setprio 1
	s_waitcnt lgkmcnt(0)
	v_mfma_f32_16x16x32_bf16 v[56:59], v[142:145], v[192:195], v[56:59]
	v_mfma_f32_16x16x32_bf16 v[52:55], v[156:159], v[192:195], v[52:55]
	v_mfma_f32_16x16x32_bf16 v[40:43], v[142:145], v[200:203], v[40:43]
	v_mfma_f32_16x16x32_bf16 v[36:39], v[156:159], v[200:203], v[36:39]
	v_mfma_f32_16x16x32_bf16 v[24:27], v[142:145], v[216:219], v[24:27]
	v_mfma_f32_16x16x32_bf16 v[20:23], v[156:159], v[216:219], v[20:23]
	v_mfma_f32_16x16x32_bf16 v[8:11], v[142:145], v[224:227], v[8:11]
	v_mfma_f32_16x16x32_bf16 v[4:7], v[156:159], v[224:227], v[4:7]
	v_mfma_f32_16x16x32_bf16 v[56:59], v[152:155], v[196:199], v[56:59]
	v_mfma_f32_16x16x32_bf16 v[52:55], v[172:175], v[196:199], v[52:55]
	v_mfma_f32_16x16x32_bf16 v[40:43], v[152:155], v[212:215], v[40:43]
	v_mfma_f32_16x16x32_bf16 v[36:39], v[172:175], v[212:215], v[36:39]
	v_mfma_f32_16x16x32_bf16 v[24:27], v[152:155], v[220:223], v[24:27]
	v_mfma_f32_16x16x32_bf16 v[20:23], v[172:175], v[220:223], v[20:23]
	v_mfma_f32_16x16x32_bf16 v[8:11], v[152:155], v[228:231], v[8:11]
	v_mfma_f32_16x16x32_bf16 v[4:7], v[172:175], v[228:231], v[4:7]
	s_setprio 0
	s_setprio 1
	v_mfma_f32_16x16x32_bf16 v[64:67], v[176:179], v[192:195], v[64:67]
	v_mfma_f32_16x16x32_bf16 v[60:63], v[184:187], v[192:195], v[60:63]
	v_mfma_f32_16x16x32_bf16 v[48:51], v[176:179], v[200:203], v[48:51]
	v_mfma_f32_16x16x32_bf16 v[44:47], v[184:187], v[200:203], v[44:47]
	v_mfma_f32_16x16x32_bf16 v[32:35], v[176:179], v[216:219], v[32:35]
	v_mfma_f32_16x16x32_bf16 v[28:31], v[184:187], v[216:219], v[28:31]
	v_mfma_f32_16x16x32_bf16 v[16:19], v[176:179], v[224:227], v[16:19]
	v_mfma_f32_16x16x32_bf16 v[12:15], v[184:187], v[224:227], v[12:15]
	v_mfma_f32_16x16x32_bf16 v[64:67], v[180:183], v[196:199], v[64:67]
	v_mfma_f32_16x16x32_bf16 v[60:63], v[188:191], v[196:199], v[60:63]
	v_mfma_f32_16x16x32_bf16 v[48:51], v[180:183], v[212:215], v[48:51]
	v_mfma_f32_16x16x32_bf16 v[44:47], v[188:191], v[212:215], v[44:47]
	v_mfma_f32_16x16x32_bf16 v[32:35], v[180:183], v[220:223], v[32:35]
	v_mfma_f32_16x16x32_bf16 v[28:31], v[188:191], v[220:223], v[28:31]
	v_mfma_f32_16x16x32_bf16 v[16:19], v[180:183], v[228:231], v[16:19]
	v_mfma_f32_16x16x32_bf16 v[12:15], v[188:191], v[228:231], v[12:15]
	s_setprio 0
	s_barrier
	s_add_i32 s56, s56, 2
	s_add_u32 s2, s2, 0x100
	s_addc_u32 s3, s3, 0
	s_cmp_gt_u32 s56, 29
	s_cbranch_scc0 .LBB0_1051
	s_and_b64 vcc, exec, s[10:11]
	s_cbranch_vccz .LBB0_1054
	s_barrier

; #define PG8_STAGE(bufoff, gbase, voff) do { _Pragma("unroll") for (int _i = 0; _i < 2; ++_i) \
;         __builtin_amdgcn_global_load_lds((const unsigned*)((const char*)(gbase) + (voff)[_i]), (PG8_LAS unsigned*)(lds + (bufoff) + ldsw + _i * 8192), 16, 0, 0); } while (0)
; #define PG8_LDA(dst, b, h) do { _Pragma("unroll") for (int m = 0; m < 4; ++m) _Pragma("unroll") for (int k = 0; k < 2; ++k) dst[m][k] = *(const PG8_LAS bf16x8*)(lds + PG8_SA(b, h) + aoff + m * 2048 + k * 1024); } while (0)
; #define PG8_LDB(dst, b, h) do { _Pragma("unroll") for (int n = 0; n < 2; ++n) _Pragma("unroll") for (int k = 0; k < 2; ++k) dst[n][k] = *(const PG8_LAS bf16x8*)(lds + PG8_SB(b, h) + boff + n * 2048 + k * 1024); } while (0)
; #define PG8_MMA(ai, bj, At, Bt) do { __builtin_amdgcn_s_setprio(1); _Pragma("unroll") for (int m = 0; m < 4; ++m) _Pragma("unroll") for (int n = 0; n < 2; ++n) _Pragma("unroll") for (int k = 0; k < 2; ++k) \
;         acc[ai][bj][m][n] = __builtin_amdgcn_mfma_f32_16x16x32_bf16(Bt[n][k], At[m][k], acc[ai][bj][m][n], 0, 0, 0); __builtin_amdgcn_s_setprio(0); } while (0)
; #define PG8_WAIT_V(n) asm volatile("s_waitcnt vmcnt(" #n ")" ::: "memory")
; #define PG8_WAIT_L(n) asm volatile("s_waitcnt lgkmcnt(" #n ")" ::: "memory")
; #define PG8_BAR __builtin_amdgcn_s_barrier()
; #define PG8_SCHED __builtin_amdgcn_sched_barrier(0)
; template <class Epi, class Sched, bool ALIGN_EPI = false, bool SP2 = false>
; __device__ __forceinline__ void gemm_phase(PG8_LAS unsigned char* lds, const Gemm g, const Sched& S, const Epi& E) {
;     ...
;             PG8_LDB(B0, 0, 0); PG8_LDB(B1, 0, 1); PG8_SCHED; PG8_LDA(At, 0, 0); PG8_STAGE(PG8_SA(1, 1), a1 + hstep, voffA);
;             PG8_WAIT_V(8); PG8_WAIT_L(0); PG8_BAR; PG8_MMA(0, 0, At, B0); PG8_MMA(0, 1, At, B1); PG8_BAR; PG8_SCHED;
;     ...
; #pragma unroll
;         for (int a = 0; a < 2; ++a)
; #pragma unroll
;             for (int b = 0; b < 2; ++b)
; #pragma unroll
;                 for (int m = 0; m < 4; ++m)
; #pragma unroll
;                     for (int n = 0; n < 2; ++n) acc[a][b][m][n] = (f32x4){0.f, 0.f, 0.f, 0.f};
;         cur = nxt; cA = nA; cB = nB; ++ui;
.LBB0_1277:
	s_add_u32 s61, s2, 0x100
	v_mov_b32_e32 v4, 0
	s_addc_u32 s66, s3, 0
	s_mov_b32 s67, -2
	s_mov_b64 s[2:3], 0
	s_waitcnt lgkmcnt(0)
	v_mov_b32_e32 v5, v4
	v_mov_b32_e32 v6, v4
	v_mov_b32_e32 v7, v4
	v_mov_b32_e32 v8, v4
	v_mov_b32_e32 v9, v4
	v_mov_b32_e32 v10, v4
	v_mov_b32_e32 v11, v4
	v_mov_b32_e32 v20, v4
	v_mov_b32_e32 v21, v4
	v_mov_b32_e32 v22, v4
	v_mov_b32_e32 v23, v4
	v_mov_b32_e32 v24, v4
	v_mov_b32_e32 v25, v4
	v_mov_b32_e32 v26, v4
	v_mov_b32_e32 v27, v4
	v_mov_b32_e32 v36, v4
	v_mov_b32_e32 v37, v4
	v_mov_b32_e32 v38, v4
	v_mov_b32_e32 v39, v4
	v_mov_b32_e32 v40, v4
	v_mov_b32_e32 v41, v4
	v_mov_b32_e32 v42, v4
	v_mov_b32_e32 v43, v4
	v_mov_b32_e32 v52, v4
	v_mov_b32_e32 v53, v4
	v_mov_b32_e32 v54, v4
	v_mov_b32_e32 v55, v4
	v_mov_b32_e32 v56, v4
	v_mov_b32_e32 v57, v4
	v_mov_b32_e32 v58, v4
	v_mov_b32_e32 v59, v4
	v_mov_b32_e32 v12, v4
	v_mov_b32_e32 v13, v4
	v_mov_b32_e32 v14, v4
	v_mov_b32_e32 v15, v4
	v_mov_b32_e32 v16, v4
	v_mov_b32_e32 v17, v4
	v_mov_b32_e32 v18, v4
	v_mov_b32_e32 v19, v4
	v_mov_b32_e32 v28, v4
	v_mov_b32_e32 v29, v4
	v_mov_b32_e32 v30, v4
	v_mov_b32_e32 v31, v4
	v_mov_b32_e32 v32, v4
	v_mov_b32_e32 v33, v4
	v_mov_b32_e32 v34, v4
	v_mov_b32_e32 v35, v4
	v_mov_b32_e32 v44, v4
	v_mov_b32_e32 v45, v4
	v_mov_b32_e32 v46, v4
	v_mov_b32_e32 v47, v4
	v_mov_b32_e32 v48, v4
	v_mov_b32_e32 v49, v4
	v_mov_b32_e32 v50, v4
	v_mov_b32_e32 v51, v4
	v_mov_b32_e32 v60, v4
	v_mov_b32_e32 v61, v4
	v_mov_b32_e32 v62, v4
	v_mov_b32_e32 v63, v4
	v_mov_b32_e32 v64, v4
	v_mov_b32_e32 v65, v4
	v_mov_b32_e32 v66, v4
	v_mov_b32_e32 v67, v4
	v_mov_b32_e32 v68, v4
	v_mov_b32_e32 v69, v4
	v_mov_b32_e32 v70, v4
	v_mov_b32_e32 v71, v4
	v_mov_b32_e32 v72, v4
	v_mov_b32_e32 v73, v4
	v_mov_b32_e32 v74, v4
	v_mov_b32_e32 v75, v4
	v_mov_b32_e32 v84, v4
	v_mov_b32_e32 v85, v4
	v_mov_b32_e32 v86, v4
	v_mov_b32_e32 v87, v4
	v_mov_b32_e32 v88, v4
	v_mov_b32_e32 v89, v4
	v_mov_b32_e32 v90, v4
	v_mov_b32_e32 v91, v4
	v_mov_b32_e32 v100, v4
	v_mov_b32_e32 v101, v4
	v_mov_b32_e32 v102, v4
	v_mov_b32_e32 v103, v4
	v_mov_b32_e32 v104, v4
	v_mov_b32_e32 v105, v4
	v_mov_b32_e32 v106, v4
	v_mov_b32_e32 v107, v4
	v_mov_b32_e32 v116, v4
	v_mov_b32_e32 v117, v4
	v_mov_b32_e32 v118, v4
	v_mov_b32_e32 v119, v4
	v_mov_b32_e32 v120, v4
	v_mov_b32_e32 v121, v4
	v_mov_b32_e32 v122, v4
	v_mov_b32_e32 v123, v4
	v_mov_b32_e32 v76, v4
	v_mov_b32_e32 v77, v4
	v_mov_b32_e32 v78, v4
	v_mov_b32_e32 v79, v4
	v_mov_b32_e32 v80, v4
	v_mov_b32_e32 v81, v4
	v_mov_b32_e32 v82, v4
	v_mov_b32_e32 v83, v4
	v_mov_b32_e32 v92, v4
	v_mov_b32_e32 v93, v4
	v_mov_b32_e32 v94, v4
	v_mov_b32_e32 v95, v4
	v_mov_b32_e32 v96, v4
	v_mov_b32_e32 v97, v4
	v_mov_b32_e32 v98, v4
	v_mov_b32_e32 v99, v4
	v_mov_b32_e32 v108, v4
	v_mov_b32_e32 v109, v4
	v_mov_b32_e32 v110, v4
	v_mov_b32_e32 v111, v4
	v_mov_b32_e32 v112, v4
	v_mov_b32_e32 v113, v4
	v_mov_b32_e32 v114, v4
	v_mov_b32_e32 v115, v4
	v_mov_b32_e32 v128, v4
	v_mov_b32_e32 v129, v4
	v_mov_b32_e32 v130, v4
	v_mov_b32_e32 v131, v4
	v_mov_b32_e32 v132, v4
	v_mov_b32_e32 v133, v4
	v_mov_b32_e32 v134, v4
	v_mov_b32_e32 v135, v4
	v_add_u32_e32 v168, 0x10000, v3
	v_add_u32_e32 v169, 0x14000, v3
	v_add_u32_e32 v170, 0x18000, v3
	v_add_u32_e32 v171, 0x1c000, v3
.LBB0_1278:
	s_add_u32 s38, s93, s2
	s_addc_u32 s39, s95, s3
	s_add_u32 s38, s38, 0x1da00100
	s_addc_u32 s39, s39, 0
	s_add_u32 s68, s61, s2
	s_addc_u32 s69, s66, s3
	s_add_i32 s70, 0, 0x10000
	s_cmpk_eq_i32 s2, 0x2b00
	s_cselect_b32 s47, s35, s39
	s_cselect_b32 s46, s34, s38
	s_cselect_b32 s39, s43, s69
	s_cselect_b32 s38, s42, s68
	s_add_i32 s71, 0, 0x14000
	ds_read_b128 v[124:127], v168
	ds_read_b128 v[136:139], v168 offset:1024
	ds_read_b128 v[140:143], v168 offset:2048
	ds_read_b128 v[144:147], v168 offset:3072
	ds_read_b128 v[148:151], v169
	ds_read_b128 v[152:155], v169 offset:1024
	ds_read_b128 v[156:159], v169 offset:2048
	ds_read_b128 v[182:185], v169 offset:3072
	v_lshl_add_u64 v[202:203], v[178:179], 0, s[2:3]
	s_add_i32 m0, s49, 0xc000
	ds_read_b128 v[186:189], v214
	ds_read_b128 v[190:193], v214 offset:1024
	ds_read_b128 v[194:197], v214 offset:2048
	ds_read_b128 v[198:201], v214 offset:3072
	ds_read_b128 v[216:219], v214 offset:4096
	ds_read_b128 v[220:223], v214 offset:5120
	ds_read_b128 v[224:227], v214 offset:6144
	ds_read_b128 v[228:231], v214 offset:7168
	global_load_lds_dwordx4 v[202:203], off
	v_lshl_add_u64 v[202:203], v[180:181], 0, s[2:3]
	s_add_i32 m0, s49, 0xe000
	s_nop 0
	global_load_lds_dwordx4 v[202:203], off
	s_waitcnt vmcnt(8)
	s_waitcnt lgkmcnt(0)
	s_barrier
; #define PG8_STAGE(bufoff, gbase, voff) do { _Pragma("unroll") for (int _i = 0; _i < 2; ++_i) \
;         __builtin_amdgcn_global_load_lds((const unsigned*)((const char*)(gbase) + (voff)[_i]), (PG8_LAS unsigned*)(lds + (bufoff) + ldsw + _i * 8192), 16, 0, 0); } while (0)
; #define PG8_LDA(dst, b, h) do { _Pragma("unroll") for (int m = 0; m < 4; ++m) _Pragma("unroll") for (int k = 0; k < 2; ++k) dst[m][k] = *(const PG8_LAS bf16x8*)(lds + PG8_SA(b, h) + aoff + m * 2048 + k * 1024); } while (0)
; #define PG8_LDB(dst, b, h) do { _Pragma("unroll") for (int n = 0; n < 2; ++n) _Pragma("unroll") for (int k = 0; k < 2; ++k) dst[n][k] = *(const PG8_LAS bf16x8*)(lds + PG8_SB(b, h) + boff + n * 2048 + k * 1024); } while (0)
; #define PG8_MMA(ai, bj, At, Bt) do { __builtin_amdgcn_s_setprio(1); _Pragma("unroll") for (int m = 0; m < 4; ++m) _Pragma("unroll") for (int n = 0; n < 2; ++n) _Pragma("unroll") for (int k = 0; k < 2; ++k) \
;         acc[ai][bj][m][n] = __builtin_amdgcn_mfma_f32_16x16x32_bf16(Bt[n][k], At[m][k], acc[ai][bj][m][n], 0, 0, 0); __builtin_amdgcn_s_setprio(0); } while (0)
; #define PG8_WAIT_V(n) asm volatile("s_waitcnt vmcnt(" #n ")" ::: "memory")
; #define PG8_WAIT_L(n) asm volatile("s_waitcnt lgkmcnt(" #n ")" ::: "memory")
; #define PG8_BAR __builtin_amdgcn_s_barrier()
; #define PG8_SCHED __builtin_amdgcn_sched_barrier(0)
; template <class Epi, class Sched, bool ALIGN_EPI = false, bool SP2 = false>
; __device__ __forceinline__ void gemm_phase(PG8_LAS unsigned char* lds, const Gemm g, const Sched& S, const Epi& E) {
;     ...
;             PG8_LDB(B0, 0, 0); PG8_LDB(B1, 0, 1); PG8_SCHED; PG8_LDA(At, 0, 0); PG8_STAGE(PG8_SA(1, 1), a1 + hstep, voffA);
;             PG8_WAIT_V(8); PG8_WAIT_L(0); PG8_BAR; PG8_MMA(0, 0, At, B0); PG8_MMA(0, 1, At, B1); PG8_BAR; PG8_SCHED;
;             PG8_LDA(At, 0, 1); PG8_STAGE(PG8_SB(0, 0), b2, voffB); PG8_STAGE(PG8_SB(0, 1), b2 + hstep, voffB); PG8_STAGE(PG8_SA(0, 0), a2, voffA);
;             PG8_WAIT_V(8); PG8_WAIT_L(0); PG8_BAR; PG8_MMA(1, 0, At, B0); PG8_MMA(1, 1, At, B1); PG8_BAR; PG8_SCHED;
	s_setprio 1
	s_waitcnt lgkmcnt(0)
	v_mfma_f32_16x16x32_bf16 v[132:135], v[124:127], v[186:189], v[132:135]
	v_mfma_f32_16x16x32_bf16 v[128:131], v[140:143], v[186:189], v[128:131]
	v_mfma_f32_16x16x32_bf16 v[112:115], v[124:127], v[194:197], v[112:115]
	v_mfma_f32_16x16x32_bf16 v[108:111], v[140:143], v[194:197], v[108:111]
	v_mfma_f32_16x16x32_bf16 v[96:99], v[124:127], v[216:219], v[96:99]
	v_mfma_f32_16x16x32_bf16 v[92:95], v[140:143], v[216:219], v[92:95]
	v_mfma_f32_16x16x32_bf16 v[80:83], v[124:127], v[224:227], v[80:83]
	v_mfma_f32_16x16x32_bf16 v[76:79], v[140:143], v[224:227], v[76:79]
	v_mfma_f32_16x16x32_bf16 v[132:135], v[136:139], v[190:193], v[132:135]
	v_mfma_f32_16x16x32_bf16 v[128:131], v[144:147], v[190:193], v[128:131]
	v_mfma_f32_16x16x32_bf16 v[112:115], v[136:139], v[198:201], v[112:115]
	v_mfma_f32_16x16x32_bf16 v[108:111], v[144:147], v[198:201], v[108:111]
	v_mfma_f32_16x16x32_bf16 v[96:99], v[136:139], v[220:223], v[96:99]
	v_mfma_f32_16x16x32_bf16 v[92:95], v[144:147], v[220:223], v[92:95]
	v_mfma_f32_16x16x32_bf16 v[80:83], v[136:139], v[228:231], v[80:83]
	v_mfma_f32_16x16x32_bf16 v[76:79], v[144:147], v[228:231], v[76:79]
	s_setprio 0
	s_setprio 1
	v_mfma_f32_16x16x32_bf16 v[120:123], v[148:151], v[186:189], v[120:123]
	v_mfma_f32_16x16x32_bf16 v[116:119], v[156:159], v[186:189], v[116:119]
	v_mfma_f32_16x16x32_bf16 v[104:107], v[148:151], v[194:197], v[104:107]
	v_mfma_f32_16x16x32_bf16 v[100:103], v[156:159], v[194:197], v[100:103]
	v_mfma_f32_16x16x32_bf16 v[88:91], v[148:151], v[216:219], v[88:91]
	v_mfma_f32_16x16x32_bf16 v[84:87], v[156:159], v[216:219], v[84:87]
	v_mfma_f32_16x16x32_bf16 v[72:75], v[148:151], v[224:227], v[72:75]
	v_mfma_f32_16x16x32_bf16 v[68:71], v[156:159], v[224:227], v[68:71]
	v_mfma_f32_16x16x32_bf16 v[120:123], v[152:155], v[190:193], v[120:123]
	v_mfma_f32_16x16x32_bf16 v[116:119], v[182:185], v[190:193], v[116:119]
	v_mfma_f32_16x16x32_bf16 v[104:107], v[152:155], v[198:201], v[104:107]
	v_mfma_f32_16x16x32_bf16 v[100:103], v[182:185], v[198:201], v[100:103]
	v_mfma_f32_16x16x32_bf16 v[88:91], v[152:155], v[220:223], v[88:91]
	v_mfma_f32_16x16x32_bf16 v[84:87], v[182:185], v[220:223], v[84:87]
	v_mfma_f32_16x16x32_bf16 v[72:75], v[152:155], v[228:231], v[72:75]
	v_mfma_f32_16x16x32_bf16 v[68:71], v[182:185], v[228:231], v[68:71]
	s_setprio 0
	s_barrier
	s_add_i32 s68, s70, s48
	s_add_u32 s98, s38, 0x80
	s_addc_u32 s99, s39, 0
	s_mov_b32 m0, s68
	ds_read_b128 v[186:189], v214 offset:16384
	ds_read_b128 v[190:193], v214 offset:17408
	ds_read_b128 v[194:197], v214 offset:18432
	ds_read_b128 v[198:201], v214 offset:19456
	ds_read_b128 v[216:219], v214 offset:20480
	ds_read_b128 v[220:223], v214 offset:21504
	ds_read_b128 v[224:227], v214 offset:22528
	ds_read_b128 v[228:231], v214 offset:23552
	global_load_lds_dwordx4 v174, s[38:39]
	s_add_i32 m0, s68, 0x2000
	s_add_u32 s68, s38, 0x160000
	s_addc_u32 s69, s39, 0
	s_add_i32 s70, s71, s48
	global_load_lds_dwordx4 v0, s[38:39]
	s_mov_b32 m0, s70
	s_add_u32 s100, s46, 0x80
	s_addc_u32 s101, s47, 0
	s_nop 0
	global_load_lds_dwordx4 v174, s[68:69]
	s_add_i32 m0, s70, 0x2000
	s_nop 0
	global_load_lds_dwordx4 v0, s[68:69]
	s_mov_b32 m0, s49
	s_nop 0
	global_load_lds_dwordx4 v176, s[46:47]
	s_mov_b32 m0, s50
	s_nop 0
	global_load_lds_dwordx4 v172, s[46:47]
	s_waitcnt vmcnt(8)
	s_waitcnt lgkmcnt(0)
	s_barrier
	s_setprio 1
	s_waitcnt lgkmcnt(0)
	v_mfma_f32_16x16x32_bf16 v[64:67], v[124:127], v[186:189], v[64:67]
	v_mfma_f32_16x16x32_bf16 v[60:63], v[140:143], v[186:189], v[60:63]
	v_mfma_f32_16x16x32_bf16 v[48:51], v[124:127], v[194:197], v[48:51]
	v_mfma_f32_16x16x32_bf16 v[44:47], v[140:143], v[194:197], v[44:47]
	v_mfma_f32_16x16x32_bf16 v[32:35], v[124:127], v[216:219], v[32:35]
	v_mfma_f32_16x16x32_bf16 v[28:31], v[140:143], v[216:219], v[28:31]
	v_mfma_f32_16x16x32_bf16 v[16:19], v[124:127], v[224:227], v[16:19]
	v_mfma_f32_16x16x32_bf16 v[12:15], v[140:143], v[224:227], v[12:15]
	v_mfma_f32_16x16x32_bf16 v[64:67], v[136:139], v[190:193], v[64:67]
	v_mfma_f32_16x16x32_bf16 v[60:63], v[144:147], v[190:193], v[60:63]
	v_mfma_f32_16x16x32_bf16 v[48:51], v[136:139], v[198:201], v[48:51]
	v_mfma_f32_16x16x32_bf16 v[44:47], v[144:147], v[198:201], v[44:47]
	v_mfma_f32_16x16x32_bf16 v[32:35], v[136:139], v[220:223], v[32:35]
	v_mfma_f32_16x16x32_bf16 v[28:31], v[144:147], v[220:223], v[28:31]
	v_mfma_f32_16x16x32_bf16 v[16:19], v[136:139], v[228:231], v[16:19]
	v_mfma_f32_16x16x32_bf16 v[12:15], v[144:147], v[228:231], v[12:15]
	s_setprio 0
	s_setprio 1
	v_mfma_f32_16x16x32_bf16 v[56:59], v[148:151], v[186:189], v[56:59]
	v_mfma_f32_16x16x32_bf16 v[52:55], v[156:159], v[186:189], v[52:55]
	v_mfma_f32_16x16x32_bf16 v[40:43], v[148:151], v[194:197], v[40:43]
	v_mfma_f32_16x16x32_bf16 v[36:39], v[156:159], v[194:197], v[36:39]
	v_mfma_f32_16x16x32_bf16 v[24:27], v[148:151], v[216:219], v[24:27]
	v_mfma_f32_16x16x32_bf16 v[20:23], v[156:159], v[216:219], v[20:23]
	v_mfma_f32_16x16x32_bf16 v[8:11], v[148:151], v[224:227], v[8:11]
	v_mfma_f32_16x16x32_bf16 v[4:7], v[156:159], v[224:227], v[4:7]
	v_mfma_f32_16x16x32_bf16 v[56:59], v[152:155], v[190:193], v[56:59]
	v_mfma_f32_16x16x32_bf16 v[52:55], v[182:185], v[190:193], v[52:55]
	v_mfma_f32_16x16x32_bf16 v[40:43], v[152:155], v[198:201], v[40:43]
	v_mfma_f32_16x16x32_bf16 v[36:39], v[182:185], v[198:201], v[36:39]
	v_mfma_f32_16x16x32_bf16 v[24:27], v[152:155], v[220:223], v[24:27]
	v_mfma_f32_16x16x32_bf16 v[20:23], v[182:185], v[220:223], v[20:23]
	v_mfma_f32_16x16x32_bf16 v[8:11], v[152:155], v[228:231], v[8:11]
	v_mfma_f32_16x16x32_bf16 v[4:7], v[182:185], v[228:231], v[4:7]
	s_setprio 0
	s_barrier
; #define PG8_STAGE(bufoff, gbase, voff) do { _Pragma("unroll") for (int _i = 0; _i < 2; ++_i) \
;         __builtin_amdgcn_global_load_lds((const unsigned*)((const char*)(gbase) + (voff)[_i]), (PG8_LAS unsigned*)(lds + (bufoff) + ldsw + _i * 8192), 16, 0, 0); } while (0)
; #define PG8_LDA(dst, b, h) do { _Pragma("unroll") for (int m = 0; m < 4; ++m) _Pragma("unroll") for (int k = 0; k < 2; ++k) dst[m][k] = *(const PG8_LAS bf16x8*)(lds + PG8_SA(b, h) + aoff + m * 2048 + k * 1024); } while (0)
; #define PG8_LDB(dst, b, h) do { _Pragma("unroll") for (int n = 0; n < 2; ++n) _Pragma("unroll") for (int k = 0; k < 2; ++k) dst[n][k] = *(const PG8_LAS bf16x8*)(lds + PG8_SB(b, h) + boff + n * 2048 + k * 1024); } while (0)
; #define PG8_MMA(ai, bj, At, Bt) do { __builtin_amdgcn_s_setprio(1); _Pragma("unroll") for (int m = 0; m < 4; ++m) _Pragma("unroll") for (int n = 0; n < 2; ++n) _Pragma("unroll") for (int k = 0; k < 2; ++k) \
;         acc[ai][bj][m][n] = __builtin_amdgcn_mfma_f32_16x16x32_bf16(Bt[n][k], At[m][k], acc[ai][bj][m][n], 0, 0, 0); __builtin_amdgcn_s_setprio(0); } while (0)
; #define PG8_WAIT_V(n) asm volatile("s_waitcnt vmcnt(" #n ")" ::: "memory")
; #define PG8_WAIT_L(n) asm volatile("s_waitcnt lgkmcnt(" #n ")" ::: "memory")
; #define PG8_BAR __builtin_amdgcn_s_barrier()
; #define PG8_SCHED __builtin_amdgcn_sched_barrier(0)
; template <class Epi, class Sched, bool ALIGN_EPI = false, bool SP2 = false>
; __device__ __forceinline__ void gemm_phase(PG8_LAS unsigned char* lds, const Gemm g, const Sched& S, const Epi& E) {
;     ...
;             PG8_WAIT_V(8); PG8_WAIT_L(0); PG8_BAR; PG8_MMA(1, 0, At, B0); PG8_MMA(1, 1, At, B1); PG8_BAR; PG8_SCHED;
;             PG8_LDB(B0, 1, 0); PG8_LDB(B1, 1, 1); PG8_SCHED; PG8_LDA(At, 1, 0); PG8_STAGE(PG8_SA(0, 1), a2 + hstep, voffA);
;             PG8_WAIT_V(8); PG8_WAIT_L(0); PG8_BAR; PG8_MMA(0, 0, At, B0); PG8_MMA(0, 1, At, B1); PG8_BAR; PG8_SCHED;
;             PG8_LDA(At, 1, 1); PG8_STAGE(PG8_SB(1, 0), b3, voffB); PG8_STAGE(PG8_SB(1, 1), b3 + hstep, voffB); PG8_STAGE(PG8_SA(1, 0), a3, voffA);
;             PG8_WAIT_V(8); PG8_WAIT_L(0); PG8_BAR; PG8_MMA(1, 0, At, B0); PG8_MMA(1, 1, At, B1); PG8_BAR; PG8_SCHED;
	s_add_i32 s68, 0, 0x18000
	s_add_i32 s69, 0, 0x1c000
	ds_read_b128 v[124:127], v170
	ds_read_b128 v[136:139], v170 offset:1024
	ds_read_b128 v[140:143], v170 offset:2048
	ds_read_b128 v[144:147], v170 offset:3072
	ds_read_b128 v[148:151], v171
	ds_read_b128 v[152:155], v171 offset:1024
	ds_read_b128 v[156:159], v171 offset:2048
	ds_read_b128 v[182:185], v171 offset:3072
	s_add_u32 s46, s46, 0x160000
	s_addc_u32 s47, s47, 0
	s_mov_b32 m0, s51
	ds_read_b128 v[186:189], v214 offset:32768
	ds_read_b128 v[190:193], v214 offset:33792
	ds_read_b128 v[194:197], v214 offset:34816
	ds_read_b128 v[198:201], v214 offset:35840
	ds_read_b128 v[216:219], v214 offset:36864
	ds_read_b128 v[220:223], v214 offset:37888
	ds_read_b128 v[224:227], v214 offset:38912
	ds_read_b128 v[228:231], v214 offset:39936
	global_load_lds_dwordx4 v176, s[46:47]
	s_mov_b32 m0, s52
	s_nop 0
	global_load_lds_dwordx4 v172, s[46:47]
	s_waitcnt vmcnt(8)
	s_waitcnt lgkmcnt(0)
	s_barrier
	s_setprio 1
	s_waitcnt lgkmcnt(0)
	v_mfma_f32_16x16x32_bf16 v[132:135], v[124:127], v[186:189], v[132:135]
	v_mfma_f32_16x16x32_bf16 v[128:131], v[140:143], v[186:189], v[128:131]
	v_mfma_f32_16x16x32_bf16 v[112:115], v[124:127], v[194:197], v[112:115]
	v_mfma_f32_16x16x32_bf16 v[108:111], v[140:143], v[194:197], v[108:111]
	v_mfma_f32_16x16x32_bf16 v[96:99], v[124:127], v[216:219], v[96:99]
	v_mfma_f32_16x16x32_bf16 v[92:95], v[140:143], v[216:219], v[92:95]
	v_mfma_f32_16x16x32_bf16 v[80:83], v[124:127], v[224:227], v[80:83]
	v_mfma_f32_16x16x32_bf16 v[76:79], v[140:143], v[224:227], v[76:79]
	v_mfma_f32_16x16x32_bf16 v[132:135], v[136:139], v[190:193], v[132:135]
	v_mfma_f32_16x16x32_bf16 v[128:131], v[144:147], v[190:193], v[128:131]
	v_mfma_f32_16x16x32_bf16 v[112:115], v[136:139], v[198:201], v[112:115]
	v_mfma_f32_16x16x32_bf16 v[108:111], v[144:147], v[198:201], v[108:111]
	v_mfma_f32_16x16x32_bf16 v[96:99], v[136:139], v[220:223], v[96:99]
	v_mfma_f32_16x16x32_bf16 v[92:95], v[144:147], v[220:223], v[92:95]
	v_mfma_f32_16x16x32_bf16 v[80:83], v[136:139], v[228:231], v[80:83]
	v_mfma_f32_16x16x32_bf16 v[76:79], v[144:147], v[228:231], v[76:79]
	s_setprio 0
	s_setprio 1
	v_mfma_f32_16x16x32_bf16 v[120:123], v[148:151], v[186:189], v[120:123]
	v_mfma_f32_16x16x32_bf16 v[116:119], v[156:159], v[186:189], v[116:119]
	v_mfma_f32_16x16x32_bf16 v[104:107], v[148:151], v[194:197], v[104:107]
	v_mfma_f32_16x16x32_bf16 v[100:103], v[156:159], v[194:197], v[100:103]
	v_mfma_f32_16x16x32_bf16 v[88:91], v[148:151], v[216:219], v[88:91]
	v_mfma_f32_16x16x32_bf16 v[84:87], v[156:159], v[216:219], v[84:87]
	v_mfma_f32_16x16x32_bf16 v[72:75], v[148:151], v[224:227], v[72:75]
	v_mfma_f32_16x16x32_bf16 v[68:71], v[156:159], v[224:227], v[68:71]
	v_mfma_f32_16x16x32_bf16 v[120:123], v[152:155], v[190:193], v[120:123]
	v_mfma_f32_16x16x32_bf16 v[116:119], v[182:185], v[190:193], v[116:119]
	v_mfma_f32_16x16x32_bf16 v[104:107], v[152:155], v[198:201], v[104:107]
	v_mfma_f32_16x16x32_bf16 v[100:103], v[182:185], v[198:201], v[100:103]
	v_mfma_f32_16x16x32_bf16 v[88:91], v[152:155], v[220:223], v[88:91]
	v_mfma_f32_16x16x32_bf16 v[84:87], v[182:185], v[220:223], v[84:87]
	v_mfma_f32_16x16x32_bf16 v[72:75], v[152:155], v[228:231], v[72:75]
	v_mfma_f32_16x16x32_bf16 v[68:71], v[182:185], v[228:231], v[68:71]
	s_setprio 0
	s_barrier
	s_add_i32 s46, s68, s48
	s_mov_b32 m0, s46
	ds_read_b128 v[186:189], v214 offset:49152
	ds_read_b128 v[190:193], v214 offset:50176
	ds_read_b128 v[194:197], v214 offset:51200
	ds_read_b128 v[198:201], v214 offset:52224
	ds_read_b128 v[216:219], v214 offset:53248
	ds_read_b128 v[220:223], v214 offset:54272
	ds_read_b128 v[224:227], v214 offset:55296
	ds_read_b128 v[228:231], v214 offset:56320
	global_load_lds_dwordx4 v174, s[98:99]
	s_add_i32 m0, s46, 0x2000
	s_add_u32 s38, s38, 0x160080
	s_addc_u32 s39, s39, 0
	s_add_i32 s46, s69, s48
	global_load_lds_dwordx4 v0, s[98:99]
	s_mov_b32 m0, s46
	s_nop 0
	global_load_lds_dwordx4 v174, s[38:39]
	s_add_i32 m0, s46, 0x2000
	s_nop 0
	global_load_lds_dwordx4 v0, s[38:39]
	s_mov_b32 m0, s53
	s_nop 0
	global_load_lds_dwordx4 v176, s[100:101]
	s_mov_b32 m0, s57
	s_nop 0
	global_load_lds_dwordx4 v172, s[100:101]
	s_waitcnt vmcnt(8)
	s_waitcnt lgkmcnt(0)
	s_barrier
	s_setprio 1
	s_waitcnt lgkmcnt(0)
	v_mfma_f32_16x16x32_bf16 v[64:67], v[124:127], v[186:189], v[64:67]
	v_mfma_f32_16x16x32_bf16 v[60:63], v[140:143], v[186:189], v[60:63]
	v_mfma_f32_16x16x32_bf16 v[48:51], v[124:127], v[194:197], v[48:51]
	v_mfma_f32_16x16x32_bf16 v[44:47], v[140:143], v[194:197], v[44:47]
	v_mfma_f32_16x16x32_bf16 v[32:35], v[124:127], v[216:219], v[32:35]
	v_mfma_f32_16x16x32_bf16 v[28:31], v[140:143], v[216:219], v[28:31]
	v_mfma_f32_16x16x32_bf16 v[16:19], v[124:127], v[224:227], v[16:19]
	v_mfma_f32_16x16x32_bf16 v[12:15], v[140:143], v[224:227], v[12:15]
	v_mfma_f32_16x16x32_bf16 v[64:67], v[136:139], v[190:193], v[64:67]
	v_mfma_f32_16x16x32_bf16 v[60:63], v[144:147], v[190:193], v[60:63]
	v_mfma_f32_16x16x32_bf16 v[48:51], v[136:139], v[198:201], v[48:51]
	v_mfma_f32_16x16x32_bf16 v[44:47], v[144:147], v[198:201], v[44:47]
	v_mfma_f32_16x16x32_bf16 v[32:35], v[136:139], v[220:223], v[32:35]
	v_mfma_f32_16x16x32_bf16 v[28:31], v[144:147], v[220:223], v[28:31]
	v_mfma_f32_16x16x32_bf16 v[16:19], v[136:139], v[228:231], v[16:19]
	v_mfma_f32_16x16x32_bf16 v[12:15], v[144:147], v[228:231], v[12:15]
	s_setprio 0
	s_setprio 1
	v_mfma_f32_16x16x32_bf16 v[56:59], v[148:151], v[186:189], v[56:59]
	v_mfma_f32_16x16x32_bf16 v[52:55], v[156:159], v[186:189], v[52:55]
	v_mfma_f32_16x16x32_bf16 v[40:43], v[148:151], v[194:197], v[40:43]
	v_mfma_f32_16x16x32_bf16 v[36:39], v[156:159], v[194:197], v[36:39]
	v_mfma_f32_16x16x32_bf16 v[24:27], v[148:151], v[216:219], v[24:27]
	v_mfma_f32_16x16x32_bf16 v[20:23], v[156:159], v[216:219], v[20:23]
	v_mfma_f32_16x16x32_bf16 v[8:11], v[148:151], v[224:227], v[8:11]
	v_mfma_f32_16x16x32_bf16 v[4:7], v[156:159], v[224:227], v[4:7]
	v_mfma_f32_16x16x32_bf16 v[56:59], v[152:155], v[190:193], v[56:59]
	v_mfma_f32_16x16x32_bf16 v[52:55], v[182:185], v[190:193], v[52:55]
	v_mfma_f32_16x16x32_bf16 v[40:43], v[152:155], v[198:201], v[40:43]
	v_mfma_f32_16x16x32_bf16 v[36:39], v[182:185], v[198:201], v[36:39]
	v_mfma_f32_16x16x32_bf16 v[24:27], v[152:155], v[220:223], v[24:27]
	v_mfma_f32_16x16x32_bf16 v[20:23], v[182:185], v[220:223], v[20:23]
	v_mfma_f32_16x16x32_bf16 v[8:11], v[152:155], v[228:231], v[8:11]
	v_mfma_f32_16x16x32_bf16 v[4:7], v[182:185], v[228:231], v[4:7]
	s_setprio 0
	s_barrier
	s_add_i32 s67, s67, 2
	s_add_u32 s2, s2, 0x100
	s_addc_u32 s3, s3, 0
	s_cmpk_gt_u32 s67, 0x55
	s_cbranch_scc0 .LBB0_1278
	s_and_b64 vcc, exec, s[12:13]
	s_cbranch_vccz .LBB0_1281
	s_barrier
